# prep gate pass: dead denormal/finite fixups of log(1+exp(-|z|)) removed (argument in [1,2]); scan: k_end^T fragments direct to registers
# baseline (speedup 1.0000x reference)
; #define LAS __attribute__((address_space(3)))
; __device__ __forceinline__ void gla_prep_phase(const Ctx& c, int j, LAS unsigned char* lds) {
;     ...
;         for (int ii = 0; ii < 32; ++ii) { const int i = half * 32 + ii; float z = bias;
; #pragma unroll
;             for (int r = 0; r < 16; r += 4) { const f32x4 l4 = *(const LAS f32x4*)(LR + i * 16 + r); z += l4.x * up[r] + l4.y * up[r + 1] + l4.z * up[r + 2] + l4.w * up[r + 3]; }
;             const float ls = fminf(z, 0.f) - __logf(1.f + __expf(-fabsf(z)));
;             const bool valid = (ch > 0) || (i >= 48);
;             run += valid ? ls * (1.f / 16.f) : 0.f; CUM[i * 256 + d] = run; }
.LBB0_673:
	v_add_u32_e32 v173, 0, v150
	ds_read_b128 v[154:157], v173
	ds_read_b128 v[158:161], v173 offset:16
	ds_read_b128 v[162:165], v173 offset:32
	ds_read_b128 v[166:169], v173 offset:48
	v_add_u32_e32 v172, s0, v53
	s_waitcnt lgkmcnt(3)
	v_mov_b32_e32 v170, v154
	s_waitcnt lgkmcnt(2)
	v_mov_b32_e32 v171, v158
	v_mov_b32_e32 v158, v155
	v_pk_mul_f32 v[154:155], v[0:1], v[158:159]
	v_mov_b32_e32 v158, v156
	v_pk_fma_f32 v[154:155], v[2:3], v[170:171], v[154:155]
	v_mov_b32_e32 v159, v160
	v_pk_fma_f32 v[154:155], v[4:5], v[158:159], v[154:155]
	v_mov_b32_e32 v160, v157
	v_pk_fma_f32 v[154:155], v[6:7], v[160:161], v[154:155]
	v_add_u32_e32 v171, 0, v151
	v_add_f32_e32 v153, v105, v154
	v_add_f32_e32 v153, v153, v155
	s_waitcnt lgkmcnt(0)
	v_mov_b32_e32 v155, v166
	v_mov_b32_e32 v166, v163
	v_mov_b32_e32 v154, v162
	v_pk_mul_f32 v[156:157], v[8:9], v[166:167]
	v_add_u32_e32 v174, 2, v172
	v_pk_fma_f32 v[154:155], v[10:11], v[154:155], v[156:157]
	v_mov_b32_e32 v156, v164
	v_mov_b32_e32 v157, v168
	v_pk_fma_f32 v[154:155], v[12:13], v[156:157], v[154:155]
	v_mov_b32_e32 v168, v165
	v_pk_fma_f32 v[154:155], v[14:15], v[168:169], v[154:155]
	s_add_i32 s0, s0, 4
	v_add_f32_e32 v153, v153, v154
	v_add_f32_e32 v153, v153, v155
	v_min_f32_e32 v154, 0, v153
	v_mul_f32_e64 v153, |v153|, s6
	v_exp_f32_e32 v153, v153
	v_add_u32_e32 v151, 0x1000, v151
	v_add_u32_e32 v150, 0x100, v150
	v_add_f32_e32 v153, 1.0, v153
	v_log_f32_e32 v153, v153
	s_nop 0
	v_mul_f32_e32 v155, 0x3f317217, v153
	v_fma_f32 v155, v153, s8, -v155
	v_fmac_f32_e32 v155, 0x3377d1cf, v153
	v_fmac_f32_e32 v155, 0x3f317217, v153
	v_sub_f32_e32 v153, v154, v155
	v_cmp_lt_i32_e32 vcc, 47, v172
	s_or_b64 vcc, s[96:97], vcc
	v_mul_f32_e32 v153, 0x3d800000, v153
	v_cndmask_b32_e32 v153, 0, v153, vcc
	v_add_f32_e32 v170, v152, v153
	v_add_u32_e32 v152, 0x12000, v171
	ds_write_b32 v152, v170
	ds_read_b128 v[152:155], v173 offset:64
	ds_read_b128 v[156:159], v173 offset:80
	ds_read_b128 v[160:163], v173 offset:96
	ds_read_b128 v[164:167], v173 offset:112
	s_waitcnt lgkmcnt(3)
	v_mov_b32_e32 v168, v152
	s_waitcnt lgkmcnt(2)
	v_mov_b32_e32 v169, v156
	v_mov_b32_e32 v156, v153
	v_pk_mul_f32 v[152:153], v[0:1], v[156:157]
	v_mov_b32_e32 v156, v154
	v_pk_fma_f32 v[152:153], v[2:3], v[168:169], v[152:153]
	v_mov_b32_e32 v157, v158
	v_pk_fma_f32 v[152:153], v[4:5], v[156:157], v[152:153]
	v_mov_b32_e32 v158, v155
	v_pk_fma_f32 v[152:153], v[6:7], v[158:159], v[152:153]
	s_nop 0
	v_add_f32_e32 v152, v105, v152
	v_add_f32_e32 v156, v152, v153
	s_waitcnt lgkmcnt(0)
	v_mov_b32_e32 v153, v164
	v_mov_b32_e32 v164, v161
	v_mov_b32_e32 v152, v160
	v_pk_mul_f32 v[154:155], v[8:9], v[164:165]
	s_nop 0
	v_pk_fma_f32 v[152:153], v[10:11], v[152:153], v[154:155]
	v_mov_b32_e32 v154, v162
	v_mov_b32_e32 v155, v166
	v_pk_fma_f32 v[152:153], v[12:13], v[154:155], v[152:153]
	v_mov_b32_e32 v166, v163
	v_pk_fma_f32 v[152:153], v[14:15], v[166:167], v[152:153]
	s_nop 0
	v_add_f32_e32 v152, v156, v152
	v_add_f32_e32 v152, v152, v153
	v_min_f32_e32 v153, 0, v152
	v_mul_f32_e64 v152, |v152|, s6
	v_exp_f32_e32 v152, v152
	s_nop 0
	v_add_f32_e32 v152, 1.0, v152
	v_log_f32_e32 v152, v152
	s_nop 0
	v_mul_f32_e32 v154, 0x3f317217, v152
	v_fma_f32 v154, v152, s8, -v154
	v_fmac_f32_e32 v154, 0x3377d1cf, v152
	v_fmac_f32_e32 v154, 0x3f317217, v152
	v_sub_f32_e32 v152, v153, v154
	v_cmp_lt_i32_e32 vcc, 46, v172
	s_or_b64 vcc, s[96:97], vcc
	v_mul_f32_e32 v152, 0x3d800000, v152
	v_cndmask_b32_e32 v152, 0, v152, vcc
	v_add_f32_e32 v170, v170, v152
	v_add_u32_e32 v152, 0x12400, v171
	ds_write_b32 v152, v170
	ds_read_b128 v[152:155], v173 offset:128
	ds_read_b128 v[156:159], v173 offset:144
	ds_read_b128 v[160:163], v173 offset:160
	ds_read_b128 v[164:167], v173 offset:176
	v_add_u32_e32 v172, 3, v172
	s_waitcnt lgkmcnt(3)
	v_mov_b32_e32 v168, v152
	s_waitcnt lgkmcnt(2)
	v_mov_b32_e32 v169, v156
	v_mov_b32_e32 v156, v153
	v_pk_mul_f32 v[152:153], v[0:1], v[156:157]
	v_mov_b32_e32 v156, v154
	v_pk_fma_f32 v[152:153], v[2:3], v[168:169], v[152:153]
	v_mov_b32_e32 v157, v158
	v_pk_fma_f32 v[152:153], v[4:5], v[156:157], v[152:153]
	v_mov_b32_e32 v158, v155
	v_pk_fma_f32 v[152:153], v[6:7], v[158:159], v[152:153]
	s_nop 0
	v_add_f32_e32 v152, v105, v152
	v_add_f32_e32 v156, v152, v153
	s_waitcnt lgkmcnt(0)
	v_mov_b32_e32 v153, v164
	v_mov_b32_e32 v164, v161
	v_mov_b32_e32 v152, v160
	v_pk_mul_f32 v[154:155], v[8:9], v[164:165]
	s_nop 0
	v_pk_fma_f32 v[152:153], v[10:11], v[152:153], v[154:155]
	v_mov_b32_e32 v154, v162
	v_mov_b32_e32 v155, v166
	v_pk_fma_f32 v[152:153], v[12:13], v[154:155], v[152:153]
	v_mov_b32_e32 v166, v163
	v_pk_fma_f32 v[152:153], v[14:15], v[166:167], v[152:153]
	s_nop 0
	v_add_f32_e32 v152, v156, v152
	v_add_f32_e32 v152, v152, v153
	v_min_f32_e32 v153, 0, v152
	v_mul_f32_e64 v152, |v152|, s6
	v_exp_f32_e32 v152, v152
	s_nop 0
	v_add_f32_e32 v152, 1.0, v152
	v_log_f32_e32 v152, v152
	s_nop 0
	v_mul_f32_e32 v154, 0x3f317217, v152
	v_fma_f32 v154, v152, s8, -v154
	v_fmac_f32_e32 v154, 0x3377d1cf, v152
	v_fmac_f32_e32 v154, 0x3f317217, v152
	v_sub_f32_e32 v152, v153, v154
	v_cmp_lt_i32_e32 vcc, 47, v174
	s_or_b64 vcc, s[96:97], vcc
	v_mul_f32_e32 v152, 0x3d800000, v152
	v_cndmask_b32_e32 v152, 0, v152, vcc
	v_add_f32_e32 v170, v170, v152
	v_add_u32_e32 v152, 0x12800, v171
	ds_write_b32 v152, v170
	ds_read_b128 v[152:155], v173 offset:192
	ds_read_b128 v[156:159], v173 offset:208
	ds_read_b128 v[160:163], v173 offset:224
	ds_read_b128 v[164:167], v173 offset:240
	s_waitcnt lgkmcnt(3)
	v_mov_b32_e32 v168, v152
	s_waitcnt lgkmcnt(2)
; __device__ __forceinline__ unsigned cvt_pk_bf16(float lo, float hi) { unsigned r; asm volatile("v_cvt_pk_bf16_f32 %0, %1, %2" : "=v"(r) : "v"(lo), "v"(hi)); return r; }
; #define LAS __attribute__((address_space(3)))
; __device__ __forceinline__ void gla_prep_phase(const Ctx& c, int j, LAS unsigned char* lds) {
;     ...
;             run += valid ? ls * (1.f / 16.f) : 0.f; CUM[i * 256 + d] = run; }
;         TOT[half * 256 + d] = run;
;         __syncthreads();
;     ...
;             const int dq = (c.tid & 63) * 4, i0 = (c.tid >> 6) * 8, hf = i0 >> 5;
;             const f32x4 t0 = *(const LAS f32x4*)(TOT + dq), t1 = *(const LAS f32x4*)(TOT + 256 + dq), total = t0 + t1;
;             const f32x4 off0 = hf ? t0 : (f32x4){0.f, 0.f, 0.f, 0.f}, sbase = hf ? t1 : total;
;             f32x4 etot; etot.x = __expf(total.x); etot.y = __expf(total.y); etot.z = __expf(total.z); etot.w = __expf(total.w);
;             f32x4 prev = (i0 & 31) ? *(const LAS f32x4*)(CUM + (i0 - 1) * 256 + dq) : (f32x4){0.f, 0.f, 0.f, 0.f};
;             float kf[4][8];
; #pragma unroll
;             for (int e = 0; e < 8; ++e) { const int i = i0 + e;
;                 const f32x4 incl = *(const LAS f32x4*)(CUM + i * 256 + dq);
;                 const f32x4 cum = (dir == 0) ? (off0 + incl) : (sbase - prev); prev = incl;
;                 const u32x2 qw = *(const LAS u32x2*)(QL + i * 528 + dq * 2), kw = *(const LAS u32x2*)(KL + i * 528 + dq * 2);
;                 const float qv[4] = {__uint_as_float(qw.x << 16), __uint_as_float(qw.x & 0xffff0000u), __uint_as_float(qw.y << 16), __uint_as_float(qw.y & 0xffff0000u)};
;                 const float kv[4] = {__uint_as_float(kw.x << 16), __uint_as_float(kw.x & 0xffff0000u), __uint_as_float(kw.y << 16), __uint_as_float(kw.y & 0xffff0000u)};
;                 float qd[4], ki[4];
; #pragma unroll
;                 for (int jx = 0; jx < 4; ++jx) { const float ec = __expf(cum[jx]), rc = __builtin_amdgcn_rcpf(ec);
;                     qd[jx] = qv[jx] * ec * (1.f / 16.f); ki[jx] = kv[jx] * rc; kf[jx][e] = ki[jx] * etot[jx]; }
;                 *(LAS u32x2*)(QL + i * 528 + dq * 2) = (u32x2){pg8::cvt_pk_bf16(qd[0], qd[1]), pg8::cvt_pk_bf16(qd[2], qd[3])};
;                 *(LAS u32x2*)(KL + i * 528 + dq * 2) = (u32x2){pg8::cvt_pk_bf16(ki[0], ki[1]), pg8::cvt_pk_bf16(ki[2], ki[3])}; }
	v_mov_b32_e32 v169, v156
	v_mov_b32_e32 v156, v153
	v_pk_mul_f32 v[152:153], v[0:1], v[156:157]
	v_mov_b32_e32 v156, v154
	v_pk_fma_f32 v[152:153], v[2:3], v[168:169], v[152:153]
	v_mov_b32_e32 v157, v158
	v_pk_fma_f32 v[152:153], v[4:5], v[156:157], v[152:153]
	v_mov_b32_e32 v158, v155
	v_pk_fma_f32 v[152:153], v[6:7], v[158:159], v[152:153]
	s_nop 0
	v_add_f32_e32 v152, v105, v152
	v_add_f32_e32 v156, v152, v153
	s_waitcnt lgkmcnt(0)
	v_mov_b32_e32 v153, v164
	v_mov_b32_e32 v164, v161
	v_mov_b32_e32 v152, v160
	v_pk_mul_f32 v[154:155], v[8:9], v[164:165]
	s_nop 0
	v_pk_fma_f32 v[152:153], v[10:11], v[152:153], v[154:155]
	v_mov_b32_e32 v154, v162
	v_mov_b32_e32 v155, v166
	v_pk_fma_f32 v[152:153], v[12:13], v[154:155], v[152:153]
	v_mov_b32_e32 v166, v163
	v_pk_fma_f32 v[152:153], v[14:15], v[166:167], v[152:153]
	s_nop 0
	v_add_f32_e32 v152, v156, v152
	v_add_f32_e32 v152, v152, v153
	v_min_f32_e32 v153, 0, v152
	v_mul_f32_e64 v152, |v152|, s6
	v_exp_f32_e32 v152, v152
	s_nop 0
	v_add_f32_e32 v152, 1.0, v152
	v_log_f32_e32 v152, v152
	s_nop 0
	v_mul_f32_e32 v154, 0x3f317217, v152
	v_fma_f32 v154, v152, s8, -v154
	v_fmac_f32_e32 v154, 0x3377d1cf, v152
	v_fmac_f32_e32 v154, 0x3f317217, v152
	v_sub_f32_e32 v152, v153, v154
	v_cmp_lt_i32_e32 vcc, 47, v172
	s_or_b64 vcc, s[96:97], vcc
	v_mul_f32_e32 v152, 0x3d800000, v152
	v_cndmask_b32_e32 v152, 0, v152, vcc
	v_add_f32_e32 v152, v170, v152
	v_add_u32_e32 v153, 0x12c00, v171
	s_cmp_eq_u32 s0, 32
	ds_write_b32 v153, v152
	s_cbranch_scc0 .LBB0_673
	ds_write_b32 v91, v152 offset:4096
	s_waitcnt lgkmcnt(0)
	s_barrier
	ds_read_b128 v[0:3], v128 offset:4096
	ds_read_b128 v[8:11], v128 offset:5120
	v_mov_b32_e32 v4, 0
	v_mov_b32_e32 v5, 0
	v_mov_b32_e32 v6, 0
	v_mov_b32_e32 v7, 0
	s_and_saveexec_b64 s[0:1], s[38:39]
	ds_read_b128 v[4:7], v132
	s_or_b64 exec, exec, s[0:1]
	s_waitcnt lgkmcnt(0)
	v_pk_add_f32 v[150:151], v[0:1], v[8:9]
	s_lshl_b32 s0, s94, 4
	v_pk_add_f32 v[154:155], v[2:3], v[10:11]
	v_cndmask_b32_e64 v14, v9, v151, s[36:37]
	v_cndmask_b32_e64 v9, v3, 0, s[36:37]
	v_add_u32_e32 v3, v130, v129
	s_add_i32 s0, s0, s13
	v_cndmask_b32_e64 v12, v11, v155, s[36:37]
	v_cndmask_b32_e64 v13, v10, v154, s[36:37]
	v_cndmask_b32_e64 v15, v8, v150, s[36:37]
	v_cndmask_b32_e64 v11, v1, 0, s[36:37]
	v_cndmask_b32_e64 v10, v0, 0, s[36:37]
	v_mul_f32_e32 v0, 0x3fb8aa3b, v150
	v_mul_f32_e32 v1, 0x3fb8aa3b, v151
	ds_read_b128 v[150:153], v3
	s_mul_hi_i32 s1, s0, 0x41
	s_mulk_i32 s0, 0x41
	s_ashr_i32 s13, s12, 31
	s_add_u32 s94, s0, s12
	s_addc_u32 s95, s1, s13
	s_add_i32 s0, s11, 0x40f
	s_cmpk_lt_u32 s0, 0x81f
	v_cndmask_b32_e64 v8, v2, 0, s[36:37]
	v_mul_f32_e32 v2, 0x3fb8aa3b, v154
	v_mul_f32_e32 v3, 0x3fb8aa3b, v155
	s_waitcnt lgkmcnt(0)
	v_pk_add_f32 v[154:155], v[10:11], v[150:151]
	v_sub_f32_e32 v159, v15, v4
	v_sub_f32_e32 v160, v14, v5
	s_cselect_b64 s[54:55], -1, 0
	v_sub_f32_e32 v105, v13, v6
	v_sub_f32_e32 v158, v12, v7
	ds_read2st64_b64 v[4:7], v138 offset0:12 offset1:78
	v_cndmask_b32_e64 v155, v160, v155, s[54:55]
	v_cndmask_b32_e64 v154, v159, v154, s[54:55]
	v_mul_f32_e32 v154, 0x3fb8aa3b, v154
	v_mul_f32_e32 v155, 0x3fb8aa3b, v155
	v_exp_f32_e32 v154, v154
	v_exp_f32_e32 v155, v155
	v_pk_add_f32 v[156:157], v[8:9], v[152:153]
	s_waitcnt lgkmcnt(0)
	v_lshlrev_b32_e32 v159, 16, v6
	v_cndmask_b32_e64 v157, v158, v157, s[54:55]
	v_cndmask_b32_e64 v105, v105, v156, s[54:55]
	v_lshlrev_b32_e32 v156, 16, v4
	v_and_b32_e32 v4, 0xffff0000, v4
	v_rcp_f32_e32 v161, v154
	v_mul_f32_e32 v154, v154, v156
	v_rcp_f32_e32 v156, v155
	v_mul_f32_e32 v4, v155, v4
	v_mul_f32_e32 v105, 0x3fb8aa3b, v105
	v_mul_f32_e32 v155, 0x3fb8aa3b, v157
	v_exp_f32_e32 v105, v105
	v_exp_f32_e32 v155, v155
	v_and_b32_e32 v6, 0xffff0000, v6
	v_lshlrev_b32_e32 v158, 16, v5
	v_and_b32_e32 v5, 0xffff0000, v5
	v_mul_f32_e32 v6, v156, v6
	v_rcp_f32_e32 v156, v105
	v_rcp_f32_e32 v157, v155
	v_mul_f32_e32 v5, v155, v5
	v_mul_f32_e32 v4, 0x3d800000, v4
	v_mul_f32_e32 v105, v105, v158
	v_mul_f32_e32 v5, 0x3d800000, v5
	v_lshlrev_b32_e32 v160, 16, v7
	v_and_b32_e32 v7, 0xffff0000, v7
	v_mul_f32_e32 v154, 0x3d800000, v154
	v_mul_f32_e32 v105, 0x3d800000, v105
	v_cvt_pk_bf16_f32 v4, v154, v4
	v_cvt_pk_bf16_f32 v5, v105, v5
	v_mul_f32_e32 v159, v161, v159
	v_mul_f32_e32 v158, v156, v160
	v_mul_f32_e32 v160, v157, v7
	ds_write_b64 v138, v[4:5] offset:6144
	v_cvt_pk_bf16_f32 v4, v159, v6
	v_cvt_pk_bf16_f32 v5, v158, v160
	ds_write_b64 v138, v[4:5] offset:39936
	ds_read_b128 v[154:157], v139
	v_exp_f32_e32 v0, v0
	v_exp_f32_e32 v2, v2
	v_sub_f32_e32 v105, v15, v150
	v_sub_f32_e32 v162, v14, v151
	v_mul_f32_e32 v7, v0, v159
	v_mul_f32_e32 v5, v2, v158
	s_waitcnt lgkmcnt(0)
	v_pk_add_f32 v[158:159], v[10:11], v[154:155]
	v_add_u32_e32 v150, 16, v138
	v_cndmask_b32_e64 v105, v105, v158, s[54:55]
	v_mul_f32_e32 v105, 0x3fb8aa3b, v105
	v_exp_f32_e32 v105, v105
	v_exp_f32_e32 v3, v3
	v_sub_f32_e32 v163, v13, v152
	v_sub_f32_e32 v164, v12, v153
	ds_read2st64_b64 v[150:153], v150 offset0:13 offset1:79
	v_cndmask_b32_e64 v159, v162, v159, s[54:55]
	v_mul_f32_e32 v159, 0x3fb8aa3b, v159
	v_rcp_f32_e32 v165, v105
	v_exp_f32_e32 v159, v159
	v_mul_f32_e32 v4, v3, v160
	v_pk_add_f32 v[160:161], v[8:9], v[156:157]
	s_waitcnt lgkmcnt(0)
; __device__ __forceinline__ unsigned cvt_pk_bf16(float lo, float hi) { unsigned r; asm volatile("v_cvt_pk_bf16_f32 %0, %1, %2" : "=v"(r) : "v"(lo), "v"(hi)); return r; }
; #define LAS __attribute__((address_space(3)))
; __device__ __forceinline__ void gla_prep_phase(const Ctx& c, int j, LAS unsigned char* lds) {
;     ...
;             for (int e = 0; e < 8; ++e) { const int i = i0 + e;
;                 const f32x4 incl = *(const LAS f32x4*)(CUM + i * 256 + dq);
;                 const f32x4 cum = (dir == 0) ? (off0 + incl) : (sbase - prev); prev = incl;
;                 const u32x2 qw = *(const LAS u32x2*)(QL + i * 528 + dq * 2), kw = *(const LAS u32x2*)(KL + i * 528 + dq * 2);
;                 const float qv[4] = {__uint_as_float(qw.x << 16), __uint_as_float(qw.x & 0xffff0000u), __uint_as_float(qw.y << 16), __uint_as_float(qw.y & 0xffff0000u)};
;                 const float kv[4] = {__uint_as_float(kw.x << 16), __uint_as_float(kw.x & 0xffff0000u), __uint_as_float(kw.y << 16), __uint_as_float(kw.y & 0xffff0000u)};
;                 float qd[4], ki[4];
; #pragma unroll
;                 for (int jx = 0; jx < 4; ++jx) { const float ec = __expf(cum[jx]), rc = __builtin_amdgcn_rcpf(ec);
;                     qd[jx] = qv[jx] * ec * (1.f / 16.f); ki[jx] = kv[jx] * rc; kf[jx][e] = ki[jx] * etot[jx]; }
;                 *(LAS u32x2*)(QL + i * 528 + dq * 2) = (u32x2){pg8::cvt_pk_bf16(qd[0], qd[1]), pg8::cvt_pk_bf16(qd[2], qd[3])};
;                 *(LAS u32x2*)(KL + i * 528 + dq * 2) = (u32x2){pg8::cvt_pk_bf16(ki[0], ki[1]), pg8::cvt_pk_bf16(ki[2], ki[3])}; }
	v_lshlrev_b32_e32 v158, 16, v150
	v_cndmask_b32_e64 v160, v163, v160, s[54:55]
	v_lshlrev_b32_e32 v163, 16, v152
	v_mul_f32_e32 v105, v105, v158
	v_mul_f32_e32 v158, v165, v163
	v_rcp_f32_e32 v163, v159
	v_cndmask_b32_e64 v161, v164, v161, s[54:55]
	v_and_b32_e32 v150, 0xffff0000, v150
	v_and_b32_e32 v152, 0xffff0000, v152
	v_mul_f32_e32 v150, v159, v150
	v_mul_f32_e32 v159, 0x3fb8aa3b, v160
	v_mul_f32_e32 v160, v163, v152
	v_mul_f32_e32 v152, 0x3fb8aa3b, v161
	v_exp_f32_e32 v159, v159
	v_exp_f32_e32 v152, v152
	v_lshlrev_b32_e32 v162, 16, v151
	v_and_b32_e32 v151, 0xffff0000, v151
	v_rcp_f32_e32 v161, v159
	v_mul_f32_e32 v159, v159, v162
	v_rcp_f32_e32 v162, v152
	v_mul_f32_e32 v151, v152, v151
	v_mul_f32_e32 v150, 0x3d800000, v150
	v_mul_f32_e32 v151, 0x3d800000, v151
	v_lshlrev_b32_e32 v164, 16, v153
	v_and_b32_e32 v153, 0xffff0000, v153
	v_mul_f32_e32 v105, 0x3d800000, v105
	v_mul_f32_e32 v159, 0x3d800000, v159
	v_cvt_pk_bf16_f32 v150, v105, v150
	v_cvt_pk_bf16_f32 v151, v159, v151
	v_mul_f32_e32 v161, v161, v164
	v_mul_f32_e32 v162, v162, v153
	ds_write_b64 v138, v[150:151] offset:6672
	v_cvt_pk_bf16_f32 v150, v158, v160
	v_cvt_pk_bf16_f32 v151, v161, v162
	ds_write_b64 v138, v[150:151] offset:40464
	ds_read_b128 v[150:153], v140
	v_mul_f32_e32 v163, v0, v158
	v_mul_f32_e32 v105, v3, v162
	v_sub_f32_e32 v162, v15, v154
	v_sub_f32_e32 v166, v14, v155
	s_waitcnt lgkmcnt(0)
	v_pk_add_f32 v[158:159], v[10:11], v[150:151]
	v_add_u32_e32 v154, 32, v138
	v_cndmask_b32_e64 v158, v162, v158, s[54:55]
	v_mul_f32_e32 v158, 0x3fb8aa3b, v158
	v_exp_f32_e32 v158, v158
	v_exp_f32_e32 v1, v1
	v_sub_f32_e32 v167, v13, v156
	v_sub_f32_e32 v168, v12, v157
	ds_read2st64_b64 v[154:157], v154 offset0:14 offset1:80
	v_cndmask_b32_e64 v159, v166, v159, s[54:55]
	v_mul_f32_e32 v159, 0x3fb8aa3b, v159
	v_rcp_f32_e32 v169, v158
	v_exp_f32_e32 v159, v159
	v_mul_f32_e32 v164, v1, v160
	v_mul_f32_e32 v165, v2, v161
	v_pk_add_f32 v[160:161], v[8:9], v[152:153]
	s_waitcnt lgkmcnt(0)
	v_lshlrev_b32_e32 v162, 16, v154
	v_cndmask_b32_e64 v160, v167, v160, s[54:55]
	v_lshlrev_b32_e32 v167, 16, v156
	v_mul_f32_e32 v158, v158, v162
	v_mul_f32_e32 v162, v169, v167
	v_rcp_f32_e32 v167, v159
	v_cndmask_b32_e64 v161, v168, v161, s[54:55]
	v_and_b32_e32 v154, 0xffff0000, v154
	v_and_b32_e32 v156, 0xffff0000, v156
	v_mul_f32_e32 v154, v159, v154
	v_mul_f32_e32 v159, 0x3fb8aa3b, v160
	v_mul_f32_e32 v160, v167, v156
	v_mul_f32_e32 v156, 0x3fb8aa3b, v161
	v_exp_f32_e32 v159, v159
	v_exp_f32_e32 v156, v156
	v_lshlrev_b32_e32 v166, 16, v155
	v_and_b32_e32 v155, 0xffff0000, v155
	v_rcp_f32_e32 v161, v159
	v_mul_f32_e32 v159, v159, v166
	v_rcp_f32_e32 v166, v156
	v_mul_f32_e32 v155, v156, v155
	v_mul_f32_e32 v154, 0x3d800000, v154
	v_mul_f32_e32 v155, 0x3d800000, v155
	v_lshlrev_b32_e32 v168, 16, v157
	v_and_b32_e32 v157, 0xffff0000, v157
	v_mul_f32_e32 v158, 0x3d800000, v158
	v_mul_f32_e32 v159, 0x3d800000, v159
	v_cvt_pk_bf16_f32 v154, v158, v154
	v_cvt_pk_bf16_f32 v155, v159, v155
	v_mul_f32_e32 v161, v161, v168
	v_mul_f32_e32 v166, v166, v157
	ds_write_b64 v138, v[154:155] offset:7200
	v_cvt_pk_bf16_f32 v154, v162, v160
	v_cvt_pk_bf16_f32 v155, v161, v166
	ds_write_b64 v138, v[154:155] offset:40992
	ds_read_b128 v[154:157], v141
	v_sub_f32_e32 v169, v15, v150
	v_sub_f32_e32 v170, v14, v151
	v_add_u32_e32 v150, 48, v138
	v_sub_f32_e32 v171, v13, v152
	s_waitcnt lgkmcnt(0)
	v_pk_add_f32 v[158:159], v[10:11], v[154:155]
	v_sub_f32_e32 v172, v12, v153
	v_cndmask_b32_e64 v158, v169, v158, s[54:55]
	v_mul_f32_e32 v158, 0x3fb8aa3b, v158
	v_exp_f32_e32 v158, v158
	ds_read2st64_b64 v[150:153], v150 offset0:15 offset1:81
	v_cndmask_b32_e64 v159, v170, v159, s[54:55]
	v_mul_f32_e32 v159, 0x3fb8aa3b, v159
	v_rcp_f32_e32 v173, v158
	v_exp_f32_e32 v159, v159
	v_mul_f32_e32 v167, v1, v160
	v_mul_f32_e32 v168, v2, v161
	v_pk_add_f32 v[160:161], v[8:9], v[156:157]
	s_waitcnt lgkmcnt(0)
	v_lshlrev_b32_e32 v169, 16, v150
	v_cndmask_b32_e64 v160, v171, v160, s[54:55]
	v_lshlrev_b32_e32 v171, 16, v152
	v_mul_f32_e32 v158, v158, v169
	v_mul_f32_e32 v169, v173, v171
	v_rcp_f32_e32 v171, v159
	v_cndmask_b32_e64 v161, v172, v161, s[54:55]
	v_and_b32_e32 v150, 0xffff0000, v150
	v_and_b32_e32 v152, 0xffff0000, v152
	v_mul_f32_e32 v150, v159, v150
	v_mul_f32_e32 v159, 0x3fb8aa3b, v160
	v_mul_f32_e32 v160, v171, v152
	v_mul_f32_e32 v152, 0x3fb8aa3b, v161
	v_exp_f32_e32 v159, v159
	v_exp_f32_e32 v152, v152
	v_lshlrev_b32_e32 v170, 16, v151
	v_and_b32_e32 v151, 0xffff0000, v151
	v_rcp_f32_e32 v161, v159
	v_mul_f32_e32 v159, v159, v170
	v_rcp_f32_e32 v170, v152
	v_mul_f32_e32 v151, v152, v151
	v_mul_f32_e32 v150, 0x3d800000, v150
	v_mul_f32_e32 v151, 0x3d800000, v151
	v_lshlrev_b32_e32 v172, 16, v153
	v_and_b32_e32 v153, 0xffff0000, v153
	v_mul_f32_e32 v158, 0x3d800000, v158
	v_mul_f32_e32 v159, 0x3d800000, v159
	v_cvt_pk_bf16_f32 v150, v158, v150
	v_cvt_pk_bf16_f32 v151, v159, v151
	v_mul_f32_e32 v161, v161, v172
	v_mul_f32_e32 v170, v170, v153
	ds_write_b64 v138, v[150:151] offset:7728
	v_cvt_pk_bf16_f32 v150, v169, v160
	v_cvt_pk_bf16_f32 v151, v161, v170
	ds_write_b64 v138, v[150:151] offset:41520
	ds_read_b128 v[150:153], v142
	v_sub_f32_e32 v173, v15, v154
	v_sub_f32_e32 v174, v14, v155
	v_add_u32_e32 v154, 64, v138
	v_sub_f32_e32 v175, v13, v156
	s_waitcnt lgkmcnt(0)
	v_pk_add_f32 v[158:159], v[10:11], v[150:151]
	v_sub_f32_e32 v176, v12, v157
	v_cndmask_b32_e64 v158, v173, v158, s[54:55]
	v_mul_f32_e32 v158, 0x3fb8aa3b, v158
	v_exp_f32_e32 v158, v158
	ds_read2st64_b64 v[154:157], v154 offset0:16 offset1:82
	v_cndmask_b32_e64 v159, v174, v159, s[54:55]
	v_mul_f32_e32 v159, 0x3fb8aa3b, v159
	v_rcp_f32_e32 v177, v158
	v_exp_f32_e32 v159, v159
	v_mul_f32_e32 v171, v1, v160
	v_mul_f32_e32 v172, v2, v161
	v_pk_add_f32 v[160:161], v[8:9], v[152:153]
	s_waitcnt lgkmcnt(0)
; __device__ __forceinline__ unsigned cvt_pk_bf16(float lo, float hi) { unsigned r; asm volatile("v_cvt_pk_bf16_f32 %0, %1, %2" : "=v"(r) : "v"(lo), "v"(hi)); return r; }
; #define LAS __attribute__((address_space(3)))
; __device__ __forceinline__ void gla_prep_phase(const Ctx& c, int j, LAS unsigned char* lds) {
;     ...
;             for (int e = 0; e < 8; ++e) { const int i = i0 + e;
;                 const f32x4 incl = *(const LAS f32x4*)(CUM + i * 256 + dq);
;                 const f32x4 cum = (dir == 0) ? (off0 + incl) : (sbase - prev); prev = incl;
;                 const u32x2 qw = *(const LAS u32x2*)(QL + i * 528 + dq * 2), kw = *(const LAS u32x2*)(KL + i * 528 + dq * 2);
;                 const float qv[4] = {__uint_as_float(qw.x << 16), __uint_as_float(qw.x & 0xffff0000u), __uint_as_float(qw.y << 16), __uint_as_float(qw.y & 0xffff0000u)};
;                 const float kv[4] = {__uint_as_float(kw.x << 16), __uint_as_float(kw.x & 0xffff0000u), __uint_as_float(kw.y << 16), __uint_as_float(kw.y & 0xffff0000u)};
;                 float qd[4], ki[4];
; #pragma unroll
;                 for (int jx = 0; jx < 4; ++jx) { const float ec = __expf(cum[jx]), rc = __builtin_amdgcn_rcpf(ec);
;                     qd[jx] = qv[jx] * ec * (1.f / 16.f); ki[jx] = kv[jx] * rc; kf[jx][e] = ki[jx] * etot[jx]; }
;                 *(LAS u32x2*)(QL + i * 528 + dq * 2) = (u32x2){pg8::cvt_pk_bf16(qd[0], qd[1]), pg8::cvt_pk_bf16(qd[2], qd[3])};
;                 *(LAS u32x2*)(KL + i * 528 + dq * 2) = (u32x2){pg8::cvt_pk_bf16(ki[0], ki[1]), pg8::cvt_pk_bf16(ki[2], ki[3])}; }
	v_lshlrev_b32_e32 v173, 16, v154
	v_cndmask_b32_e64 v160, v175, v160, s[54:55]
	v_lshlrev_b32_e32 v175, 16, v156
	v_mul_f32_e32 v158, v158, v173
	v_mul_f32_e32 v173, v177, v175
	v_rcp_f32_e32 v175, v159
	v_cndmask_b32_e64 v161, v176, v161, s[54:55]
	v_and_b32_e32 v154, 0xffff0000, v154
	v_and_b32_e32 v156, 0xffff0000, v156
	v_mul_f32_e32 v154, v159, v154
	v_mul_f32_e32 v159, 0x3fb8aa3b, v160
	v_mul_f32_e32 v160, v175, v156
	v_mul_f32_e32 v156, 0x3fb8aa3b, v161
	v_exp_f32_e32 v159, v159
	v_exp_f32_e32 v156, v156
	v_lshlrev_b32_e32 v174, 16, v155
	v_and_b32_e32 v155, 0xffff0000, v155
	v_rcp_f32_e32 v161, v159
	v_mul_f32_e32 v159, v159, v174
	v_rcp_f32_e32 v174, v156
	v_mul_f32_e32 v155, v156, v155
	v_mul_f32_e32 v154, 0x3d800000, v154
	v_mul_f32_e32 v155, 0x3d800000, v155
	v_lshlrev_b32_e32 v176, 16, v157
	v_and_b32_e32 v157, 0xffff0000, v157
	v_mul_f32_e32 v158, 0x3d800000, v158
	v_mul_f32_e32 v159, 0x3d800000, v159
	v_cvt_pk_bf16_f32 v154, v158, v154
	v_cvt_pk_bf16_f32 v155, v159, v155
	v_mul_f32_e32 v161, v161, v176
	v_mul_f32_e32 v174, v174, v157
	ds_write_b64 v138, v[154:155] offset:8256
	v_cvt_pk_bf16_f32 v154, v173, v160
	v_cvt_pk_bf16_f32 v155, v161, v174
	ds_write_b64 v138, v[154:155] offset:42048
	ds_read_b128 v[154:157], v143
	v_sub_f32_e32 v177, v15, v150
	v_sub_f32_e32 v178, v14, v151
	v_add_u32_e32 v150, 0x50, v138
	v_sub_f32_e32 v179, v13, v152
	s_waitcnt lgkmcnt(0)
	v_pk_add_f32 v[158:159], v[10:11], v[154:155]
	v_sub_f32_e32 v180, v12, v153
	v_cndmask_b32_e64 v158, v177, v158, s[54:55]
	v_mul_f32_e32 v158, 0x3fb8aa3b, v158
	v_exp_f32_e32 v158, v158
	ds_read2st64_b64 v[150:153], v150 offset0:17 offset1:83
	v_cndmask_b32_e64 v159, v178, v159, s[54:55]
	v_mul_f32_e32 v159, 0x3fb8aa3b, v159
	v_rcp_f32_e32 v181, v158
	v_exp_f32_e32 v159, v159
	v_mul_f32_e32 v175, v1, v160
	v_mul_f32_e32 v176, v2, v161
	v_pk_add_f32 v[160:161], v[8:9], v[156:157]
	s_waitcnt lgkmcnt(0)
	v_lshlrev_b32_e32 v177, 16, v150
	v_cndmask_b32_e64 v160, v179, v160, s[54:55]
	v_lshlrev_b32_e32 v179, 16, v152
	v_mul_f32_e32 v158, v158, v177
	v_mul_f32_e32 v177, v181, v179
	v_rcp_f32_e32 v179, v159
	v_cndmask_b32_e64 v161, v180, v161, s[54:55]
	v_and_b32_e32 v150, 0xffff0000, v150
	v_and_b32_e32 v152, 0xffff0000, v152
	v_mul_f32_e32 v150, v159, v150
	v_mul_f32_e32 v159, 0x3fb8aa3b, v160
	v_mul_f32_e32 v160, v179, v152
	v_mul_f32_e32 v152, 0x3fb8aa3b, v161
	v_exp_f32_e32 v159, v159
	v_exp_f32_e32 v152, v152
	v_lshlrev_b32_e32 v178, 16, v151
	v_and_b32_e32 v151, 0xffff0000, v151
	v_rcp_f32_e32 v161, v159
	v_mul_f32_e32 v159, v159, v178
	v_rcp_f32_e32 v178, v152
	v_mul_f32_e32 v151, v152, v151
	v_mul_f32_e32 v150, 0x3d800000, v150
	v_mul_f32_e32 v151, 0x3d800000, v151
	v_lshlrev_b32_e32 v180, 16, v153
	v_and_b32_e32 v153, 0xffff0000, v153
	v_mul_f32_e32 v158, 0x3d800000, v158
	v_mul_f32_e32 v159, 0x3d800000, v159
	v_cvt_pk_bf16_f32 v150, v158, v150
	v_cvt_pk_bf16_f32 v151, v159, v151
	v_mul_f32_e32 v161, v161, v180
	v_mul_f32_e32 v178, v178, v153
	ds_write_b64 v138, v[150:151] offset:8784
	v_cvt_pk_bf16_f32 v150, v177, v160
	v_cvt_pk_bf16_f32 v151, v161, v178
	ds_write_b64 v138, v[150:151] offset:42576
	ds_read_b128 v[150:153], v144
	v_sub_f32_e32 v181, v15, v154
	v_sub_f32_e32 v182, v14, v155
	v_add_u32_e32 v154, 0x60, v138
	v_sub_f32_e32 v183, v13, v156
	s_waitcnt lgkmcnt(0)
	v_pk_add_f32 v[158:159], v[10:11], v[150:151]
	v_sub_f32_e32 v184, v12, v157
	v_cndmask_b32_e64 v158, v181, v158, s[54:55]
	v_mul_f32_e32 v158, 0x3fb8aa3b, v158
	v_exp_f32_e32 v158, v158
	ds_read2st64_b64 v[154:157], v154 offset0:18 offset1:84
	v_cndmask_b32_e64 v159, v182, v159, s[54:55]
	v_mul_f32_e32 v159, 0x3fb8aa3b, v159
	v_rcp_f32_e32 v185, v158
	v_exp_f32_e32 v159, v159
	v_mul_f32_e32 v179, v1, v160
	v_mul_f32_e32 v180, v2, v161
	v_pk_add_f32 v[160:161], v[8:9], v[152:153]
	s_waitcnt lgkmcnt(0)
; __device__ __forceinline__ unsigned cvt_pk_bf16(float lo, float hi) { unsigned r; asm volatile("v_cvt_pk_bf16_f32 %0, %1, %2" : "=v"(r) : "v"(lo), "v"(hi)); return r; }
; #define LAS __attribute__((address_space(3)))
; __device__ __forceinline__ void gla_prep_phase(const Ctx& c, int j, LAS unsigned char* lds) {
;     ...
;             for (int e = 0; e < 8; ++e) { const int i = i0 + e;
;                 const f32x4 incl = *(const LAS f32x4*)(CUM + i * 256 + dq);
;                 const f32x4 cum = (dir == 0) ? (off0 + incl) : (sbase - prev); prev = incl;
;                 const u32x2 qw = *(const LAS u32x2*)(QL + i * 528 + dq * 2), kw = *(const LAS u32x2*)(KL + i * 528 + dq * 2);
;                 const float qv[4] = {__uint_as_float(qw.x << 16), __uint_as_float(qw.x & 0xffff0000u), __uint_as_float(qw.y << 16), __uint_as_float(qw.y & 0xffff0000u)};
;                 const float kv[4] = {__uint_as_float(kw.x << 16), __uint_as_float(kw.x & 0xffff0000u), __uint_as_float(kw.y << 16), __uint_as_float(kw.y & 0xffff0000u)};
;                 float qd[4], ki[4];
; #pragma unroll
;                 for (int jx = 0; jx < 4; ++jx) { const float ec = __expf(cum[jx]), rc = __builtin_amdgcn_rcpf(ec);
;                     qd[jx] = qv[jx] * ec * (1.f / 16.f); ki[jx] = kv[jx] * rc; kf[jx][e] = ki[jx] * etot[jx]; }
;                 *(LAS u32x2*)(QL + i * 528 + dq * 2) = (u32x2){pg8::cvt_pk_bf16(qd[0], qd[1]), pg8::cvt_pk_bf16(qd[2], qd[3])};
;                 *(LAS u32x2*)(KL + i * 528 + dq * 2) = (u32x2){pg8::cvt_pk_bf16(ki[0], ki[1]), pg8::cvt_pk_bf16(ki[2], ki[3])}; }
;             bf16_t* kdst = KET + tile * (256 * 64) + (size_t)dq * 64 + i0;
; #pragma unroll
;             for (int jx = 0; jx < 4; ++jx)
;                 *(u32x4*)(kdst + jx * 64) = (u32x4){pg8::cvt_pk_bf16(kf[jx][0], kf[jx][1]), pg8::cvt_pk_bf16(kf[jx][2], kf[jx][3]), pg8::cvt_pk_bf16(kf[jx][4], kf[jx][5]), pg8::cvt_pk_bf16(kf[jx][6], kf[jx][7])};
;             if (i0 == 0) *(f32x4*)(DEC + tile * 256 + dq) = etot;
	v_lshlrev_b32_e32 v181, 16, v154
	v_cndmask_b32_e64 v160, v183, v160, s[54:55]
	v_lshlrev_b32_e32 v183, 16, v156
	v_mul_f32_e32 v158, v158, v181
	v_mul_f32_e32 v181, v185, v183
	v_rcp_f32_e32 v183, v159
	v_cndmask_b32_e64 v161, v184, v161, s[54:55]
	v_and_b32_e32 v154, 0xffff0000, v154
	v_and_b32_e32 v156, 0xffff0000, v156
	v_mul_f32_e32 v154, v159, v154
	v_mul_f32_e32 v159, 0x3fb8aa3b, v160
	v_mul_f32_e32 v160, v183, v156
	v_mul_f32_e32 v156, 0x3fb8aa3b, v161
	v_exp_f32_e32 v159, v159
	v_exp_f32_e32 v156, v156
	v_lshlrev_b32_e32 v182, 16, v155
	v_and_b32_e32 v155, 0xffff0000, v155
	v_rcp_f32_e32 v161, v159
	v_mul_f32_e32 v159, v159, v182
	v_rcp_f32_e32 v182, v156
	v_mul_f32_e32 v155, v156, v155
	v_mul_f32_e32 v154, 0x3d800000, v154
	v_mul_f32_e32 v155, 0x3d800000, v155
	v_lshlrev_b32_e32 v184, 16, v157
	v_and_b32_e32 v157, 0xffff0000, v157
	v_mul_f32_e32 v158, 0x3d800000, v158
	v_mul_f32_e32 v159, 0x3d800000, v159
	v_cvt_pk_bf16_f32 v154, v158, v154
	v_cvt_pk_bf16_f32 v155, v159, v155
	v_mul_f32_e32 v161, v161, v184
	v_mul_f32_e32 v182, v182, v157
	ds_write_b64 v138, v[154:155] offset:9312
	v_cvt_pk_bf16_f32 v154, v181, v160
	v_cvt_pk_bf16_f32 v155, v161, v182
	ds_write_b64 v138, v[154:155] offset:43104
	ds_read_b128 v[154:157], v145
	v_sub_f32_e32 v15, v15, v150
	v_sub_f32_e32 v14, v14, v151
	v_sub_f32_e32 v13, v13, v152
	v_sub_f32_e32 v12, v12, v153
	s_waitcnt lgkmcnt(0)
	v_pk_add_f32 v[154:155], v[10:11], v[154:155]
	v_pk_add_f32 v[156:157], v[8:9], v[156:157]
	v_cndmask_b32_e64 v15, v15, v154, s[54:55]
	v_mul_f32_e32 v15, 0x3fb8aa3b, v15
	v_exp_f32_e32 v15, v15
	ds_read2st64_b64 v[8:11], v146 offset0:12 offset1:78
	v_cndmask_b32_e64 v14, v14, v155, s[54:55]
	v_mul_f32_e32 v14, 0x3fb8aa3b, v14
	v_rcp_f32_e32 v154, v15
	v_exp_f32_e32 v14, v14
	v_cndmask_b32_e64 v13, v13, v156, s[54:55]
	s_waitcnt lgkmcnt(0)
	v_lshlrev_b32_e32 v150, 16, v8
	v_lshlrev_b32_e32 v152, 16, v10
	v_mul_f32_e32 v13, 0x3fb8aa3b, v13
	v_mul_f32_e32 v15, v15, v150
	v_mul_f32_e32 v150, v154, v152
	v_rcp_f32_e32 v154, v14
	v_exp_f32_e32 v13, v13
	v_cndmask_b32_e64 v12, v12, v157, s[54:55]
	v_and_b32_e32 v10, 0xffff0000, v10
	v_mul_f32_e32 v12, 0x3fb8aa3b, v12
	v_mul_f32_e32 v10, v154, v10
	v_rcp_f32_e32 v154, v13
	v_exp_f32_e32 v12, v12
	v_lshlrev_b32_e32 v151, 16, v9
	v_lshlrev_b32_e32 v153, 16, v11
	v_and_b32_e32 v8, 0xffff0000, v8
	v_and_b32_e32 v9, 0xffff0000, v9
	v_mul_f32_e32 v13, v13, v151
	v_mul_f32_e32 v151, v154, v153
	v_rcp_f32_e32 v153, v12
	v_mul_f32_e32 v8, v14, v8
	v_mul_f32_e32 v9, v12, v9
	v_mul_f32_e32 v8, 0x3d800000, v8
	v_mul_f32_e32 v9, 0x3d800000, v9
	v_and_b32_e32 v11, 0xffff0000, v11
	v_mul_f32_e32 v15, 0x3d800000, v15
	v_mul_f32_e32 v13, 0x3d800000, v13
	v_cvt_pk_bf16_f32 v8, v15, v8
	v_cvt_pk_bf16_f32 v9, v13, v9
	s_lshl_b64 s[0:1], s[94:95], 15
	v_mul_f32_e32 v6, v1, v6
	v_mul_f32_e32 v11, v153, v11
	ds_write_b64 v146, v[8:9] offset:6144
	v_cvt_pk_bf16_f32 v8, v150, v10
	v_cvt_pk_bf16_f32 v9, v151, v11
	v_lshl_add_u64 v[12:13], v[92:93], 0, s[0:1]
	v_mul_f32_e32 v162, v0, v162
	v_mul_f32_e32 v169, v0, v169
	v_mul_f32_e32 v173, v0, v173
	v_mul_f32_e32 v177, v0, v177
	v_mul_f32_e32 v158, v0, v181
	v_mul_f32_e32 v152, v0, v150
	v_mul_f32_e32 v14, v1, v10
	v_mul_f32_e32 v153, v3, v11
	ds_write_b64 v146, v[8:9] offset:39936
	v_cvt_pk_bf16_f32 v8, v7, v163
	v_cvt_pk_bf16_f32 v9, v162, v169
	v_cvt_pk_bf16_f32 v10, v173, v177
	v_cvt_pk_bf16_f32 v11, v158, v152
	global_store_dwordx4 v[12:13], v[8:11], off
	v_cvt_pk_bf16_f32 v6, v6, v164
	v_cvt_pk_bf16_f32 v7, v167, v171
	v_mul_f32_e32 v159, v1, v160
	v_mul_f32_e32 v166, v3, v166
	v_cvt_pk_bf16_f32 v8, v175, v179
	v_cvt_pk_bf16_f32 v9, v159, v14
	global_store_dwordx4 v[12:13], v[6:9], off offset:128
	v_mul_f32_e32 v170, v3, v170
	v_mul_f32_e32 v174, v3, v174
	v_cvt_pk_bf16_f32 v6, v5, v165
	v_cvt_pk_bf16_f32 v7, v168, v172
	v_mul_f32_e32 v178, v3, v178
	v_mul_f32_e32 v160, v2, v161
	v_mul_f32_e32 v161, v3, v182
	v_mul_f32_e32 v154, v2, v151
	v_cvt_pk_bf16_f32 v8, v176, v180
	v_cvt_pk_bf16_f32 v9, v160, v154
	global_store_dwordx4 v[12:13], v[6:9], off offset:256
	v_cvt_pk_bf16_f32 v4, v4, v105
	v_cvt_pk_bf16_f32 v5, v166, v170
	s_nop 1
	v_cvt_pk_bf16_f32 v6, v174, v178
	v_cvt_pk_bf16_f32 v7, v161, v153
	global_store_dwordx4 v[12:13], v[4:7], off offset:384
	s_and_saveexec_b64 s[0:1], s[52:53]
	s_cbranch_execz .LBB0_678
	s_lshl_b64 s[12:13], s[94:95], 10
	v_lshl_add_u64 v[4:5], v[94:95], 0, s[12:13]
	global_store_dwordx4 v[4:5], v[0:3], off

.LBB0_745:
	s_or_b64 exec, exec, s[34:35]
	s_lshl_b32 s0, s78, 2
	s_and_b32 s36, s0, 28
	s_ashr_i32 s22, s78, 6
	s_add_i32 s36, s36, s22
	s_bfe_u32 s40, s36, 0x20002
	s_cmp_lt_u32 s36, 16
	s_cselect_b64 s[34:35], -1, 0
	s_and_b64 s[0:1], s[34:35], exec
	s_mul_i32 s3, s36, 0x41
	s_cselect_b32 s0, 0, 64
	s_mul_hi_i32 s2, s36, 0x41
	s_add_u32 s38, s3, s0
	s_addc_u32 s39, s2, 0
	s_lshl_b64 s[0:1], s[38:39], 15
	s_add_u32 s42, s79, s0
	v_mov_b32_e32 v44, v200
	s_addc_u32 s43, s80, s1
	s_add_u32 s0, s81, s0
	v_ashrrev_i32_e32 v45, 31, v44
	v_lshlrev_b64 v[2:3], 4, v[44:45]
	s_addc_u32 s1, s82, s1
	v_lshl_add_u64 v[4:5], s[42:43], 0, v[2:3]
	v_lshl_add_u64 v[6:7], s[0:1], 0, v[2:3]
	global_load_dwordx4 v[36:39], v[4:5], off
	global_load_dwordx4 v[28:31], v[6:7], off
	s_mov_b64 vcc, s[20:21]
	s_cbranch_vccz .Lscan_kf_a0
	v_lshrrev_b32_e32 v140, 6, v200
	v_lshlrev_b32_e32 v140, 13, v140
	v_and_b32_e32 v141, 31, v200
	v_lshl_add_u32 v140, v141, 7, v140
	v_bfe_u32 v141, v200, 5, 1
	v_lshl_add_u32 v140, v141, 4, v140
	v_lshlrev_b32_e32 v141, 4, v200
	v_sub_u32_e32 v140, v140, v141
	v_add_u32_e32 v140, 0xffff8800, v140
	v_ashrrev_i32_e32 v141, 31, v140
	v_lshl_add_u64 v[142:143], v[140:141], 0, v[6:7]
	global_load_dwordx4 v[112:115], v[142:143], off offset:-2048
	global_load_dwordx4 v[116:119], v[142:143], off offset:-2016
	global_load_dwordx4 v[120:123], v[142:143], off offset:-1984
	global_load_dwordx4 v[124:127], v[142:143], off offset:-1952
	global_load_dwordx4 v[128:131], v[142:143], off offset:2048
	global_load_dwordx4 v[132:135], v[142:143], off offset:2080
	global_load_dwordx4 v[136:139], v[142:143], off offset:2112
	global_load_dwordx4 v[140:143], v[142:143], off offset:2144
.Lscan_kf_a0:
	v_lshl_add_u64 v[4:5], v[2:3], 0, s[26:27]
	v_lshl_add_u64 v[6:7], s[42:43], 0, v[4:5]
	v_lshl_add_u64 v[4:5], s[0:1], 0, v[4:5]
	s_lshl_b64 s[44:45], s[38:39], 13
	global_load_dwordx4 v[32:35], v[6:7], off
	global_load_dwordx4 v[16:19], v[4:5], off
	v_lshl_add_u64 v[4:5], v[2:3], 0, s[28:29]
	s_add_u32 s44, s83, s44
	v_lshl_add_u64 v[6:7], s[42:43], 0, v[4:5]
	v_lshl_add_u64 v[4:5], s[0:1], 0, v[4:5]
	s_addc_u32 s45, s90, s45
	global_load_dwordx4 v[24:27], v[6:7], off
	global_load_dwordx4 v[8:11], v[4:5], off
	v_lshl_add_u64 v[4:5], v[2:3], 0, s[30:31]
	v_lshl_add_u64 v[6:7], s[42:43], 0, v[4:5]
	v_lshl_add_u64 v[4:5], s[0:1], 0, v[4:5]
	v_lshl_add_u64 v[2:3], s[44:45], 0, v[2:3]
	global_load_dwordx4 v[20:23], v[6:7], off
	s_nop 0
	global_load_dwordx4 v[4:7], v[4:5], off
	s_cmp_gt_u32 s36, 15
	global_load_dwordx4 v[12:15], v[2:3], off
	v_and_b32_e32 v1, 63, v44
	s_mov_b64 s[0:1], -1
	s_cbranch_scc0 .LBB0_747
	v_lshl_or_b32 v2, s40, 12, v1
	v_or_b32_e32 v2, 0xfc0, v2
	s_mov_b64 s[0:1], 0

; __device__ __forceinline__ int mk_tid() { int t = (int)threadIdx.x; asm volatile("" : "+v"(t)); return t; }
; __device__ __forceinline__ void gla_scan_phase(const Ctx& c, LAS unsigned char* lds) {
;     ...
;         { const int c0 = dir ? NCH - 1 : 0; SC_LOAD(c0, mk_tid()); SC_STORE(mk_tid()); SC_LOAD(dir ? NCH - 2 : 1, mk_tid()); }
.LBB0_751:
	s_or_b64 exec, exec, s[0:1]
	v_mov_b32_e32 v45, v200
	s_nop 0
	v_lshlrev_b32_e32 v1, 4, v45
	v_and_b32_e32 v2, 0x1f0, v1
	v_add_u32_e32 v2, 0, v2
	v_ashrrev_i32_e32 v3, 5, v45
	v_mad_u64_u32 v[46:47], s[0:1], v3, s95, v[2:3]
	v_and_b32_e32 v48, 0x70, v1
	s_waitcnt vmcnt(9)
	ds_write_b128 v46, v[36:39]
	v_ashrrev_i32_e32 v36, 3, v45
	v_add_u32_e32 v44, 0, v48
	v_mul_lo_u32 v37, v36, s93
	v_add_u32_e32 v3, v44, v37
	s_waitcnt vmcnt(8)
	ds_write_b128 v3, v[28:31] offset:33792
	v_add_u32_e32 v3, 0x200, v45
	v_ashrrev_i32_e32 v28, 5, v3
	v_mad_u64_u32 v[28:29], s[0:1], v28, s95, v[2:3]
	v_lshrrev_b32_e32 v3, 3, v3
	s_waitcnt vmcnt(7)
	ds_write_b128 v28, v[32:35]
	v_mad_u64_u32 v[28:29], s[0:1], v3, s93, v[44:45]
	v_add_u32_e32 v3, 0x400, v45
	s_waitcnt vmcnt(6)
	ds_write_b128 v28, v[16:19] offset:33792
	v_ashrrev_i32_e32 v16, 5, v3
	v_mad_u64_u32 v[16:17], s[0:1], v16, s95, v[2:3]
	v_lshrrev_b32_e32 v3, 3, v3
	s_waitcnt vmcnt(5)
	ds_write_b128 v16, v[24:27]
	v_mad_u64_u32 v[16:17], s[0:1], v3, s93, v[44:45]
	s_waitcnt vmcnt(4)
	ds_write_b128 v16, v[8:11] offset:33792
	v_add_u32_e32 v8, 0x600, v45
	v_ashrrev_i32_e32 v3, 5, v8
	v_mad_u64_u32 v[2:3], s[0:1], v3, s95, v[2:3]
	s_waitcnt vmcnt(3)
	ds_write_b128 v2, v[20:23]
	v_lshrrev_b32_e32 v2, 3, v8
	v_mad_u64_u32 v[2:3], s[0:1], v2, s93, v[44:45]
	s_waitcnt vmcnt(2)
	ds_write_b128 v2, v[4:7] offset:33792
	v_add3_u32 v2, s96, v37, v48
	s_waitcnt vmcnt(1)
	ds_write_b128 v2, v[12:15]
	v_lshlrev_b32_e32 v2, 1, v45
	v_and_b32_e32 v2, 0x7e, v2
	v_and_b32_e32 v3, 0xffffff8, v36
	v_add_u32_e32 v2, s94, v2
	v_mad_u64_u32 v[4:5], s[0:1], v3, s93, v[2:3]
	v_or_b32_e32 v3, 7, v36
	v_mad_u64_u32 v[2:3], s[0:1], v3, s93, v[2:3]
	v_cmp_gt_i32_e32 vcc, 64, v45
	s_waitcnt vmcnt(0)
	ds_write_b16 v4, v40
	ds_write_b16_d16_hi v4, v40 offset:144
	ds_write_b16 v4, v41 offset:288
	ds_write_b16_d16_hi v4, v41 offset:432
	ds_write_b16 v4, v42 offset:576
	ds_write_b16_d16_hi v4, v42 offset:720
	ds_write_b16 v4, v43 offset:864
	ds_write_b16_d16_hi v2, v43
	s_and_saveexec_b64 s[0:1], vcc
	v_add_u32_e32 v1, 0, v1
	v_add_u32_e32 v1, 0x1e000, v1
	ds_write_b128 v1, v[148:151]
	s_or_b64 exec, exec, s[0:1]
	s_and_b64 s[0:1], s[34:35], exec
	s_cselect_b32 s37, 1, 63
	s_add_u32 s38, s3, s37
	s_addc_u32 s39, s2, 0
	s_lshl_b64 s[0:1], s[38:39], 15
	v_mov_b32_e32 v2, v200
	s_add_u32 s44, s79, s0
	s_addc_u32 s45, s80, s1
	v_ashrrev_i32_e32 v3, 31, v2
	s_add_u32 s0, s81, s0
	v_lshlrev_b64 v[4:5], 4, v[2:3]
	s_addc_u32 s1, s82, s1
	v_lshl_add_u64 v[6:7], s[44:45], 0, v[4:5]
	v_lshl_add_u64 v[8:9], s[0:1], 0, v[4:5]
	global_load_dwordx4 v[152:155], v[6:7], off
	global_load_dwordx4 v[156:159], v[8:9], off
	s_mov_b64 vcc, s[20:21]
	s_cbranch_vccz .Lscan_kf_a1
	v_lshrrev_b32_e32 v250, 6, v200
	v_lshlrev_b32_e32 v250, 13, v250
	v_and_b32_e32 v251, 31, v200
	v_lshl_add_u32 v250, v251, 7, v250
	v_bfe_u32 v251, v200, 5, 1
	v_lshl_add_u32 v250, v251, 4, v250
	v_lshlrev_b32_e32 v251, 4, v200
	v_sub_u32_e32 v250, v250, v251
	v_add_u32_e32 v250, 0xffff8800, v250
	v_ashrrev_i32_e32 v251, 31, v250
	v_lshl_add_u64 v[252:253], v[250:251], 0, v[8:9]
	global_load_dwordx4 v[222:225], v[252:253], off offset:-2048
	global_load_dwordx4 v[226:229], v[252:253], off offset:-2016
	global_load_dwordx4 v[230:233], v[252:253], off offset:-1984
	global_load_dwordx4 v[234:237], v[252:253], off offset:-1952
	global_load_dwordx4 v[238:241], v[252:253], off offset:2048
	global_load_dwordx4 v[242:245], v[252:253], off offset:2080
	global_load_dwordx4 v[246:249], v[252:253], off offset:2112
	global_load_dwordx4 v[250:253], v[252:253], off offset:2144
.Lscan_kf_a1:
	v_lshl_add_u64 v[6:7], v[4:5], 0, s[26:27]
	v_lshl_add_u64 v[8:9], s[44:45], 0, v[6:7]
	v_lshl_add_u64 v[6:7], s[0:1], 0, v[6:7]
	global_load_dwordx4 v[160:163], v[8:9], off
	global_load_dwordx4 v[164:167], v[6:7], off
	v_lshl_add_u64 v[6:7], v[4:5], 0, s[28:29]
	v_lshl_add_u64 v[8:9], s[44:45], 0, v[6:7]
	v_lshl_add_u64 v[6:7], s[0:1], 0, v[6:7]
	global_load_dwordx4 v[168:171], v[8:9], off
	global_load_dwordx4 v[172:175], v[6:7], off
	v_lshl_add_u64 v[6:7], v[4:5], 0, s[30:31]
	v_lshl_add_u64 v[8:9], s[44:45], 0, v[6:7]
	v_lshl_add_u64 v[6:7], s[0:1], 0, v[6:7]
	s_lshl_b64 s[0:1], s[38:39], 13
	s_add_u32 s0, s83, s0
	s_addc_u32 s1, s90, s1
	v_lshl_add_u64 v[4:5], s[0:1], 0, v[4:5]
	s_lshl_b32 s0, s37, 6
	s_sub_i32 s0, s0, 64
	s_lshl_b32 s43, s40, 12
	v_and_or_b32 v1, v2, 63, s0
	v_or_b32_e32 v1, s43, v1
	v_mul_u32_u24_e32 v1, 0x1820, v1
	global_load_dwordx4 v[176:179], v[8:9], off
	global_load_dwordx4 v[180:183], v[6:7], off
	v_lshlrev_b32_e32 v6, 1, v1
	v_mov_b32_e32 v7, v0
	v_lshl_add_u64 v[6:7], s[16:17], 0, v[6:7]
	v_ashrrev_i32_e32 v1, 3, v2
	v_lshl_add_u64 v[6:7], v[6:7], 0, s[22:23]
	s_mov_b32 s37, s23
	v_and_b32_e32 v8, -8, v1
	v_lshl_add_u64 v[6:7], v[6:7], 0, s[36:37]
	v_ashrrev_i32_e32 v9, 31, v8
	v_lshl_add_u64 v[6:7], v[8:9], 1, v[6:7]
	v_add_co_u32_e32 v6, vcc, 0x1000, v6
	s_nop 1
	v_addc_co_u32_e32 v7, vcc, 0, v7, vcc
	global_load_dwordx4 v[184:187], v[4:5], off
	global_load_dwordx4 v[188:191], v[6:7], off
	v_cmp_gt_i32_e32 vcc, 64, v2
	s_and_saveexec_b64 s[0:1], vcc
	s_cbranch_execz .LBB0_755
	s_lshl_b64 s[38:39], s[38:39], 10
	s_add_u32 s38, s91, s38
	v_lshlrev_b32_e32 v2, 2, v2
	s_addc_u32 s39, s92, s39
	v_ashrrev_i32_e32 v3, 31, v2
	v_lshl_add_u64 v[2:3], v[2:3], 2, s[38:39]
	global_load_dwordx4 v[148:151], v[2:3], off

; #define LAS __attribute__((address_space(3)))
; __device__ __forceinline__ void gla_scan_phase(const Ctx& c, LAS unsigned char* lds) {
;     ...
;                 __builtin_amdgcn_s_setprio(2);
; #pragma unroll
;                 for (int t = 0; t < 4; ++t) { const int db = 2 * jj + (t >> 1);
; #pragma unroll
;                     for (int g4 = 0; g4 < 4; ++g4) { const f32x4 dv = *(const LAS f32x4*)(lds + SC_DEC + (32 * db + 8 * g4 + 4 * hi) * 4);
;                         sacc[t][4 * g4 + 0] *= dv.x; sacc[t][4 * g4 + 1] *= dv.y; sacc[t][4 * g4 + 2] *= dv.z; sacc[t][4 * g4 + 3] *= dv.w; } }
; #pragma unroll
;                 for (int ks = 0; ks < 4; ++ks) {
;                     const bf16x8 a0 = *(const LAS bf16x8*)(lds + SC_KT + (64 * jj + r32) * 144 + (ks * 16 + hi * 8) * 2);
;                     const bf16x8 a1 = *(const LAS bf16x8*)(lds + SC_KT + (64 * jj + 32 + r32) * 144 + (ks * 16 + hi * 8) * 2);
;                     const bf16x8 b0 = *(const LAS bf16x8*)(lds + SC_VT + r32 * 144 + (ks * 16 + hi * 8) * 2);
;                     const bf16x8 b1 = *(const LAS bf16x8*)(lds + SC_VT + (32 + r32) * 144 + (ks * 16 + hi * 8) * 2);
;                     sacc[0] = __builtin_amdgcn_mfma_f32_32x32x16_bf16(a0, b0, sacc[0], 0, 0, 0);
;                     sacc[1] = __builtin_amdgcn_mfma_f32_32x32x16_bf16(a0, b1, sacc[1], 0, 0, 0);
;                     sacc[2] = __builtin_amdgcn_mfma_f32_32x32x16_bf16(a1, b0, sacc[2], 0, 0, 0);
;                     sacc[3] = __builtin_amdgcn_mfma_f32_32x32x16_bf16(a1, b1, sacc[3], 0, 0, 0); }
.LBB0_758:
	s_mov_b64 s[84:85], -1
	s_and_b64 vcc, exec, s[20:21]
	s_cbranch_vccz .LBB0_760
	s_setprio 2
	s_mov_b64 s[84:85], 0
	ds_read_b128 v[80:83], v205
	ds_read_b128 v[84:87], v205 offset:32
	ds_read_b128 v[88:91], v205 offset:64
	ds_read_b128 v[92:95], v205 offset:96
	ds_read_b128 v[96:99], v205 offset:128
	ds_read_b128 v[100:103], v205 offset:160
	ds_read_b128 v[104:107], v205 offset:192
	ds_read_b128 v[108:111], v205 offset:224
	ds_read_b128 v[210:213], v207
	ds_read_b128 v[214:217], v207 offset:4608
	ds_read_b128 v[218:221], v207 offset:32
	ds_read_b128 v[2:5], v207 offset:4640
	s_waitcnt lgkmcnt(8)
	v_pk_mul_f32 v[64:65], v[64:65], v[80:81]
	v_pk_mul_f32 v[66:67], v[66:67], v[82:83]
	v_pk_mul_f32 v[68:69], v[68:69], v[84:85]
	v_pk_mul_f32 v[70:71], v[70:71], v[86:87]
	v_pk_mul_f32 v[72:73], v[72:73], v[88:89]
	v_pk_mul_f32 v[74:75], v[74:75], v[90:91]
	v_pk_mul_f32 v[76:77], v[76:77], v[92:93]
	v_pk_mul_f32 v[78:79], v[78:79], v[94:95]
	v_pk_mul_f32 v[48:49], v[48:49], v[80:81]
	v_pk_mul_f32 v[50:51], v[50:51], v[82:83]
	v_pk_mul_f32 v[52:53], v[52:53], v[84:85]
	v_pk_mul_f32 v[54:55], v[54:55], v[86:87]
	v_pk_mul_f32 v[56:57], v[56:57], v[88:89]
	v_pk_mul_f32 v[58:59], v[58:59], v[90:91]
	v_pk_mul_f32 v[60:61], v[60:61], v[92:93]
	v_pk_mul_f32 v[62:63], v[62:63], v[94:95]
	ds_read_b128 v[80:83], v207 offset:64
	ds_read_b128 v[84:87], v207 offset:4672
	ds_read_b128 v[88:91], v207 offset:96
	ds_read_b128 v[92:95], v207 offset:4704
	s_waitcnt lgkmcnt(8)
	v_pk_mul_f32 v[32:33], v[32:33], v[96:97]
	v_pk_mul_f32 v[34:35], v[34:35], v[98:99]
	v_pk_mul_f32 v[36:37], v[36:37], v[100:101]
	v_pk_mul_f32 v[38:39], v[38:39], v[102:103]
	v_pk_mul_f32 v[40:41], v[40:41], v[104:105]
	v_pk_mul_f32 v[42:43], v[42:43], v[106:107]
	v_pk_mul_f32 v[44:45], v[44:45], v[108:109]
	v_pk_mul_f32 v[46:47], v[46:47], v[110:111]
	v_pk_mul_f32 v[16:17], v[16:17], v[96:97]
	v_pk_mul_f32 v[18:19], v[18:19], v[98:99]
	v_pk_mul_f32 v[20:21], v[20:21], v[100:101]
	v_pk_mul_f32 v[22:23], v[22:23], v[102:103]
	v_pk_mul_f32 v[24:25], v[24:25], v[104:105]
	v_pk_mul_f32 v[26:27], v[26:27], v[106:107]
	v_pk_mul_f32 v[28:29], v[28:29], v[108:109]
	v_pk_mul_f32 v[30:31], v[30:31], v[110:111]
	s_waitcnt lgkmcnt(4)
	v_mfma_f32_32x32x16_bf16 v[64:79], v[112:115], v[210:213], v[64:79]
	v_mfma_f32_32x32x16_bf16 v[48:63], v[112:115], v[214:217], v[48:63]
	v_mfma_f32_32x32x16_bf16 v[32:47], v[128:131], v[210:213], v[32:47]
	v_mfma_f32_32x32x16_bf16 v[16:31], v[128:131], v[214:217], v[16:31]
	v_mfma_f32_32x32x16_bf16 v[64:79], v[116:119], v[218:221], v[64:79]
	v_mfma_f32_32x32x16_bf16 v[48:63], v[116:119], v[2:5], v[48:63]
	v_mfma_f32_32x32x16_bf16 v[32:47], v[132:135], v[218:221], v[32:47]
	v_mfma_f32_32x32x16_bf16 v[16:31], v[132:135], v[2:5], v[16:31]
	s_waitcnt lgkmcnt(0)
	v_mfma_f32_32x32x16_bf16 v[64:79], v[120:123], v[80:83], v[64:79]
	v_mfma_f32_32x32x16_bf16 v[48:63], v[120:123], v[84:87], v[48:63]
	v_mfma_f32_32x32x16_bf16 v[32:47], v[136:139], v[80:83], v[32:47]
	v_mfma_f32_32x32x16_bf16 v[16:31], v[136:139], v[84:87], v[16:31]
	v_mfma_f32_32x32x16_bf16 v[64:79], v[124:127], v[88:91], v[64:79]
	v_mfma_f32_32x32x16_bf16 v[48:63], v[124:127], v[92:95], v[48:63]
	v_mfma_f32_32x32x16_bf16 v[32:47], v[140:143], v[88:91], v[32:47]
	v_mfma_f32_32x32x16_bf16 v[16:31], v[140:143], v[92:95], v[16:31]

; __device__ __forceinline__ int mk_tid() { int t = (int)threadIdx.x; asm volatile("" : "+v"(t)); return t; }
; __device__ __forceinline__ void gla_scan_phase(const Ctx& c, LAS unsigned char* lds) {
;     ...
;             if (st + 1 < NCH) SC_STORE(mk_tid());
;             if (st + 2 < NCH) SC_LOAD(chn2, mk_tid());
.LBB0_766:
	s_cmp_eq_u32 s60, 64
	s_cbranch_scc1 .LBB0_770
	v_mov_b32_e32 v86, v200
	s_nop 0
	v_lshlrev_b32_e32 v1, 4, v86
	v_and_b32_e32 v80, 0x1f0, v1
	v_and_b32_e32 v83, 0x70, v1
	v_ashrrev_i32_e32 v87, 3, v86
	v_add_u32_e32 v80, 0, v80
	v_add_u32_e32 v82, 0, v83
	v_ashrrev_i32_e32 v81, 5, v86
	v_mul_lo_u32 v88, v87, s93
	v_mad_u64_u32 v[84:85], s[0:1], v81, s95, v[80:81]
	v_add_u32_e32 v81, v82, v88
	s_waitcnt vmcnt(0)
	ds_write_b128 v84, v[152:155]
	s_waitcnt vmcnt(8)
	v_add_u32_e32 v81, 0x200, v86
	v_ashrrev_i32_e32 v84, 5, v81
	v_mad_u64_u32 v[84:85], s[0:1], v84, s95, v[80:81]
	v_lshrrev_b32_e32 v81, 3, v81
	s_waitcnt vmcnt(7)
	ds_write_b128 v84, v[160:163]
	v_mad_u64_u32 v[84:85], s[0:1], v81, s93, v[82:83]
	v_add_u32_e32 v81, 0x400, v86
	s_waitcnt vmcnt(6)
	v_ashrrev_i32_e32 v84, 5, v81
	v_mad_u64_u32 v[84:85], s[0:1], v84, s95, v[80:81]
	v_lshrrev_b32_e32 v81, 3, v81
	s_waitcnt vmcnt(5)
	ds_write_b128 v84, v[168:171]
	v_mad_u64_u32 v[84:85], s[0:1], v81, s93, v[82:83]
	s_waitcnt vmcnt(4)
	v_add_u32_e32 v84, 0x600, v86
	v_ashrrev_i32_e32 v81, 5, v84
	v_mad_u64_u32 v[80:81], s[0:1], v81, s95, v[80:81]
	s_waitcnt vmcnt(3)
	ds_write_b128 v80, v[176:179]
	v_lshrrev_b32_e32 v80, 3, v84
	v_mad_u64_u32 v[80:81], s[0:1], v80, s93, v[82:83]
	s_waitcnt vmcnt(2)
	v_add3_u32 v80, s96, v88, v83
	s_waitcnt vmcnt(1)
	ds_write_b128 v80, v[184:187]
	v_lshlrev_b32_e32 v80, 1, v86
	v_and_b32_e32 v80, 0x7e, v80
	v_and_b32_e32 v81, 0xffffff8, v87
	v_add_u32_e32 v80, s94, v80
	v_mad_u64_u32 v[82:83], s[0:1], v81, s93, v[80:81]
	v_or_b32_e32 v81, 7, v87
	v_mad_u64_u32 v[80:81], s[0:1], v81, s93, v[80:81]
	v_cmp_gt_i32_e32 vcc, 64, v86
	s_waitcnt vmcnt(0)
	ds_write_b16 v82, v188
	ds_write_b16_d16_hi v82, v188 offset:144
	ds_write_b16 v82, v189 offset:288
	ds_write_b16_d16_hi v82, v189 offset:432
	ds_write_b16 v82, v190 offset:576
	ds_write_b16_d16_hi v82, v190 offset:720
	ds_write_b16 v82, v191 offset:864
	ds_write_b16_d16_hi v80, v191
	s_and_saveexec_b64 s[0:1], vcc
	v_add_u32_e32 v1, 0, v1
	v_add_u32_e32 v1, 0x1e000, v1
	ds_write_b128 v1, v[148:151]
	s_or_b64 exec, exec, s[0:1]
.LBB0_770:
	v_mov_b64_e32 v[112:113], v[222:223]
	v_mov_b64_e32 v[114:115], v[224:225]
	v_mov_b64_e32 v[116:117], v[226:227]
	v_mov_b64_e32 v[118:119], v[228:229]
	v_mov_b64_e32 v[120:121], v[230:231]
	v_mov_b64_e32 v[122:123], v[232:233]
	v_mov_b64_e32 v[124:125], v[234:235]
	v_mov_b64_e32 v[126:127], v[236:237]
	v_mov_b64_e32 v[128:129], v[238:239]
	v_mov_b64_e32 v[130:131], v[240:241]
	v_mov_b64_e32 v[132:133], v[242:243]
	v_mov_b64_e32 v[134:135], v[244:245]
	v_mov_b64_e32 v[136:137], v[246:247]
	v_mov_b64_e32 v[138:139], v[248:249]
	v_mov_b64_e32 v[140:141], v[250:251]
	v_mov_b64_e32 v[142:143], v[252:253]
	s_sub_i32 s37, 64, s60
	s_and_b64 s[0:1], s[34:35], exec
	s_cselect_b32 s62, s60, s37
	s_cmp_gt_u32 s60, 62
	s_cbranch_scc1 .LBB0_777
	s_add_i32 s0, s62, s56
	s_ashr_i32 s1, s0, 31
	s_add_u32 s88, s3, s0
	s_addc_u32 s89, s2, s1
	s_lshl_b64 s[64:65], s[88:89], 15
	v_mov_b32_e32 v80, v200
	s_add_u32 s66, s79, s64
	s_addc_u32 s67, s80, s65
	v_ashrrev_i32_e32 v81, 31, v80
	s_add_u32 s64, s81, s64
	v_lshlrev_b64 v[82:83], 4, v[80:81]
	s_addc_u32 s65, s82, s65
	v_lshl_add_u64 v[84:85], s[66:67], 0, v[82:83]
	v_lshl_add_u64 v[86:87], s[64:65], 0, v[82:83]
	global_load_dwordx4 v[152:155], v[84:85], off
	s_mov_b64 vcc, s[20:21]
	s_cbranch_vccz .Lscan_kf_a2
	v_lshrrev_b32_e32 v250, 6, v200
	v_lshlrev_b32_e32 v250, 13, v250
	v_and_b32_e32 v251, 31, v200
	v_lshl_add_u32 v250, v251, 7, v250
	v_bfe_u32 v251, v200, 5, 1
	v_lshl_add_u32 v250, v251, 4, v250
	v_lshlrev_b32_e32 v251, 4, v200
	v_sub_u32_e32 v250, v250, v251
	v_add_u32_e32 v250, 0xffff8800, v250
	v_ashrrev_i32_e32 v251, 31, v250
	v_lshl_add_u64 v[252:253], v[250:251], 0, v[86:87]
	global_load_dwordx4 v[222:225], v[252:253], off offset:-2048
	global_load_dwordx4 v[226:229], v[252:253], off offset:-2016
	global_load_dwordx4 v[230:233], v[252:253], off offset:-1984
	global_load_dwordx4 v[234:237], v[252:253], off offset:-1952
	global_load_dwordx4 v[238:241], v[252:253], off offset:2048
	global_load_dwordx4 v[242:245], v[252:253], off offset:2080
	global_load_dwordx4 v[246:249], v[252:253], off offset:2112
	global_load_dwordx4 v[250:253], v[252:253], off offset:2144
.Lscan_kf_a2:
	v_lshl_add_u64 v[84:85], v[82:83], 0, s[26:27]
	v_lshl_add_u64 v[86:87], s[66:67], 0, v[84:85]
	v_lshl_add_u64 v[84:85], s[64:65], 0, v[84:85]
	global_load_dwordx4 v[160:163], v[86:87], off
	v_lshl_add_u64 v[84:85], v[82:83], 0, s[28:29]
	v_lshl_add_u64 v[86:87], s[66:67], 0, v[84:85]
	v_lshl_add_u64 v[84:85], s[64:65], 0, v[84:85]
	global_load_dwordx4 v[168:171], v[86:87], off
	v_lshl_add_u64 v[84:85], v[82:83], 0, s[30:31]
	v_lshl_add_u64 v[86:87], s[66:67], 0, v[84:85]
	v_lshl_add_u64 v[84:85], s[64:65], 0, v[84:85]
	s_lshl_b64 s[64:65], s[88:89], 13
	s_add_u32 s64, s83, s64
	s_addc_u32 s65, s90, s65
	v_lshl_add_u64 v[82:83], s[64:65], 0, v[82:83]
	global_load_dwordx4 v[176:179], v[86:87], off
	global_load_dwordx4 v[184:187], v[82:83], off
	s_cmp_lg_u32 s0, 0
	v_and_b32_e32 v1, 63, v80
	s_cbranch_scc0 .LBB0_799
	s_lshl_b32 s0, s0, 6
	s_add_i32 s0, s0, s57
	v_or_b32_e32 v81, s0, v1
	s_cbranch_execnz .LBB0_774

; #define LAS __attribute__((address_space(3)))
; __device__ __forceinline__ void gla_prep_phase(const Ctx& c, int j, LAS unsigned char* lds) {
;     ...
;         for (int ii = 0; ii < 32; ++ii) { const int i = half * 32 + ii; float z = bias;
; #pragma unroll
;             for (int r = 0; r < 16; r += 4) { const f32x4 l4 = *(const LAS f32x4*)(LR + i * 16 + r); z += l4.x * up[r] + l4.y * up[r + 1] + l4.z * up[r + 2] + l4.w * up[r + 3]; }
;             const float ls = fminf(z, 0.f) - __logf(1.f + __expf(-fabsf(z)));
;             const bool valid = (ch > 0) || (i >= 48);
;             run += valid ? ls * (1.f / 16.f) : 0.f; CUM[i * 256 + d] = run; }
.LBB0_1629:
	v_add_u32_e32 v173, 0, v150
	ds_read_b128 v[154:157], v173
	ds_read_b128 v[158:161], v173 offset:16
	ds_read_b128 v[162:165], v173 offset:32
	ds_read_b128 v[166:169], v173 offset:48
	v_add_u32_e32 v172, s0, v53
	s_waitcnt lgkmcnt(3)
	v_mov_b32_e32 v170, v154
	s_waitcnt lgkmcnt(2)
	v_mov_b32_e32 v171, v158
	v_mov_b32_e32 v158, v155
	v_pk_mul_f32 v[154:155], v[0:1], v[158:159]
	v_mov_b32_e32 v158, v156
	v_pk_fma_f32 v[154:155], v[2:3], v[170:171], v[154:155]
	v_mov_b32_e32 v159, v160
	v_pk_fma_f32 v[154:155], v[4:5], v[158:159], v[154:155]
	v_mov_b32_e32 v160, v157
	v_pk_fma_f32 v[154:155], v[6:7], v[160:161], v[154:155]
	v_add_u32_e32 v171, 0, v151
	v_add_f32_e32 v153, v105, v154
	v_add_f32_e32 v153, v153, v155
	s_waitcnt lgkmcnt(0)
	v_mov_b32_e32 v155, v166
	v_mov_b32_e32 v166, v163
	v_mov_b32_e32 v154, v162
	v_pk_mul_f32 v[156:157], v[8:9], v[166:167]
	v_add_u32_e32 v174, 2, v172
	v_pk_fma_f32 v[154:155], v[10:11], v[154:155], v[156:157]
	v_mov_b32_e32 v156, v164
	v_mov_b32_e32 v157, v168
	v_pk_fma_f32 v[154:155], v[12:13], v[156:157], v[154:155]
	v_mov_b32_e32 v168, v165
	v_pk_fma_f32 v[154:155], v[14:15], v[168:169], v[154:155]
	s_add_i32 s0, s0, 4
	v_add_f32_e32 v153, v153, v154
	v_add_f32_e32 v153, v153, v155
	v_min_f32_e32 v154, 0, v153
	v_mul_f32_e64 v153, |v153|, s88
	v_exp_f32_e32 v153, v153
	v_add_u32_e32 v151, 0x1000, v151
	v_add_u32_e32 v150, 0x100, v150
	v_add_f32_e32 v153, 1.0, v153
	v_log_f32_e32 v153, v153
	s_nop 0
	v_mul_f32_e32 v155, 0x3f317217, v153
	v_fma_f32 v155, v153, s90, -v155
	v_fmac_f32_e32 v155, 0x3377d1cf, v153
	v_fmac_f32_e32 v155, 0x3f317217, v153
	v_sub_f32_e32 v153, v154, v155
	v_cmp_lt_i32_e32 vcc, 47, v172
	s_or_b64 vcc, s[66:67], vcc
	v_mul_f32_e32 v153, 0x3d800000, v153
	v_cndmask_b32_e32 v153, 0, v153, vcc
	v_add_f32_e32 v170, v152, v153
	v_add_u32_e32 v152, 0x12000, v171
	ds_write_b32 v152, v170
	ds_read_b128 v[152:155], v173 offset:64
	ds_read_b128 v[156:159], v173 offset:80
	ds_read_b128 v[160:163], v173 offset:96
	ds_read_b128 v[164:167], v173 offset:112
	s_waitcnt lgkmcnt(3)
	v_mov_b32_e32 v168, v152
	s_waitcnt lgkmcnt(2)
	v_mov_b32_e32 v169, v156
	v_mov_b32_e32 v156, v153
	v_pk_mul_f32 v[152:153], v[0:1], v[156:157]
	v_mov_b32_e32 v156, v154
	v_pk_fma_f32 v[152:153], v[2:3], v[168:169], v[152:153]
	v_mov_b32_e32 v157, v158
	v_pk_fma_f32 v[152:153], v[4:5], v[156:157], v[152:153]
	v_mov_b32_e32 v158, v155
	v_pk_fma_f32 v[152:153], v[6:7], v[158:159], v[152:153]
	s_nop 0
	v_add_f32_e32 v152, v105, v152
	v_add_f32_e32 v156, v152, v153
	s_waitcnt lgkmcnt(0)
	v_mov_b32_e32 v153, v164
	v_mov_b32_e32 v164, v161
	v_mov_b32_e32 v152, v160
	v_pk_mul_f32 v[154:155], v[8:9], v[164:165]
	s_nop 0
	v_pk_fma_f32 v[152:153], v[10:11], v[152:153], v[154:155]
	v_mov_b32_e32 v154, v162
	v_mov_b32_e32 v155, v166
	v_pk_fma_f32 v[152:153], v[12:13], v[154:155], v[152:153]
	v_mov_b32_e32 v166, v163
	v_pk_fma_f32 v[152:153], v[14:15], v[166:167], v[152:153]
	s_nop 0
	v_add_f32_e32 v152, v156, v152
	v_add_f32_e32 v152, v152, v153
	v_min_f32_e32 v153, 0, v152
	v_mul_f32_e64 v152, |v152|, s88
	v_exp_f32_e32 v152, v152
	s_nop 0
	v_add_f32_e32 v152, 1.0, v152
	v_log_f32_e32 v152, v152
	s_nop 0
	v_mul_f32_e32 v154, 0x3f317217, v152
	v_fma_f32 v154, v152, s90, -v154
	v_fmac_f32_e32 v154, 0x3377d1cf, v152
	v_fmac_f32_e32 v154, 0x3f317217, v152
	v_sub_f32_e32 v152, v153, v154
	v_cmp_lt_i32_e32 vcc, 46, v172
	s_or_b64 vcc, s[66:67], vcc
	v_mul_f32_e32 v152, 0x3d800000, v152
	v_cndmask_b32_e32 v152, 0, v152, vcc
	v_add_f32_e32 v170, v170, v152
	v_add_u32_e32 v152, 0x12400, v171
	ds_write_b32 v152, v170
	ds_read_b128 v[152:155], v173 offset:128
	ds_read_b128 v[156:159], v173 offset:144
	ds_read_b128 v[160:163], v173 offset:160
	ds_read_b128 v[164:167], v173 offset:176
	v_add_u32_e32 v172, 3, v172
	s_waitcnt lgkmcnt(3)
	v_mov_b32_e32 v168, v152
	s_waitcnt lgkmcnt(2)
	v_mov_b32_e32 v169, v156
	v_mov_b32_e32 v156, v153
	v_pk_mul_f32 v[152:153], v[0:1], v[156:157]
	v_mov_b32_e32 v156, v154
	v_pk_fma_f32 v[152:153], v[2:3], v[168:169], v[152:153]
	v_mov_b32_e32 v157, v158
	v_pk_fma_f32 v[152:153], v[4:5], v[156:157], v[152:153]
	v_mov_b32_e32 v158, v155
	v_pk_fma_f32 v[152:153], v[6:7], v[158:159], v[152:153]
	s_nop 0
	v_add_f32_e32 v152, v105, v152
	v_add_f32_e32 v156, v152, v153
	s_waitcnt lgkmcnt(0)
	v_mov_b32_e32 v153, v164
	v_mov_b32_e32 v164, v161
	v_mov_b32_e32 v152, v160
	v_pk_mul_f32 v[154:155], v[8:9], v[164:165]
	s_nop 0
	v_pk_fma_f32 v[152:153], v[10:11], v[152:153], v[154:155]
	v_mov_b32_e32 v154, v162
	v_mov_b32_e32 v155, v166
	v_pk_fma_f32 v[152:153], v[12:13], v[154:155], v[152:153]
	v_mov_b32_e32 v166, v163
	v_pk_fma_f32 v[152:153], v[14:15], v[166:167], v[152:153]
	s_nop 0
	v_add_f32_e32 v152, v156, v152
	v_add_f32_e32 v152, v152, v153
	v_min_f32_e32 v153, 0, v152
	v_mul_f32_e64 v152, |v152|, s88
	v_exp_f32_e32 v152, v152
	s_nop 0
	v_add_f32_e32 v152, 1.0, v152
	v_log_f32_e32 v152, v152
	s_nop 0
	v_mul_f32_e32 v154, 0x3f317217, v152
	v_fma_f32 v154, v152, s90, -v154
	v_fmac_f32_e32 v154, 0x3377d1cf, v152
	v_fmac_f32_e32 v154, 0x3f317217, v152
	v_sub_f32_e32 v152, v153, v154
	v_cmp_lt_i32_e32 vcc, 47, v174
	s_or_b64 vcc, s[66:67], vcc
	v_mul_f32_e32 v152, 0x3d800000, v152
	v_cndmask_b32_e32 v152, 0, v152, vcc
	v_add_f32_e32 v170, v170, v152
	v_add_u32_e32 v152, 0x12800, v171
	ds_write_b32 v152, v170
	ds_read_b128 v[152:155], v173 offset:192
	ds_read_b128 v[156:159], v173 offset:208
	ds_read_b128 v[160:163], v173 offset:224
	ds_read_b128 v[164:167], v173 offset:240
	s_waitcnt lgkmcnt(3)
	v_mov_b32_e32 v168, v152
	s_waitcnt lgkmcnt(2)
; __device__ __forceinline__ unsigned cvt_pk_bf16(float lo, float hi) { unsigned r; asm volatile("v_cvt_pk_bf16_f32 %0, %1, %2" : "=v"(r) : "v"(lo), "v"(hi)); return r; }
; #define LAS __attribute__((address_space(3)))
; __device__ __forceinline__ void gla_prep_phase(const Ctx& c, int j, LAS unsigned char* lds) {
;     ...
;             run += valid ? ls * (1.f / 16.f) : 0.f; CUM[i * 256 + d] = run; }
;         TOT[half * 256 + d] = run;
;         __syncthreads();
;     ...
;             const int dq = (c.tid & 63) * 4, i0 = (c.tid >> 6) * 8, hf = i0 >> 5;
;             const f32x4 t0 = *(const LAS f32x4*)(TOT + dq), t1 = *(const LAS f32x4*)(TOT + 256 + dq), total = t0 + t1;
;             const f32x4 off0 = hf ? t0 : (f32x4){0.f, 0.f, 0.f, 0.f}, sbase = hf ? t1 : total;
;             f32x4 etot; etot.x = __expf(total.x); etot.y = __expf(total.y); etot.z = __expf(total.z); etot.w = __expf(total.w);
;             f32x4 prev = (i0 & 31) ? *(const LAS f32x4*)(CUM + (i0 - 1) * 256 + dq) : (f32x4){0.f, 0.f, 0.f, 0.f};
;             float kf[4][8];
; #pragma unroll
;             for (int e = 0; e < 8; ++e) { const int i = i0 + e;
;                 const f32x4 incl = *(const LAS f32x4*)(CUM + i * 256 + dq);
;                 const f32x4 cum = (dir == 0) ? (off0 + incl) : (sbase - prev); prev = incl;
;                 const u32x2 qw = *(const LAS u32x2*)(QL + i * 528 + dq * 2), kw = *(const LAS u32x2*)(KL + i * 528 + dq * 2);
;                 const float qv[4] = {__uint_as_float(qw.x << 16), __uint_as_float(qw.x & 0xffff0000u), __uint_as_float(qw.y << 16), __uint_as_float(qw.y & 0xffff0000u)};
;                 const float kv[4] = {__uint_as_float(kw.x << 16), __uint_as_float(kw.x & 0xffff0000u), __uint_as_float(kw.y << 16), __uint_as_float(kw.y & 0xffff0000u)};
;                 float qd[4], ki[4];
; #pragma unroll
;                 for (int jx = 0; jx < 4; ++jx) { const float ec = __expf(cum[jx]), rc = __builtin_amdgcn_rcpf(ec);
;                     qd[jx] = qv[jx] * ec * (1.f / 16.f); ki[jx] = kv[jx] * rc; kf[jx][e] = ki[jx] * etot[jx]; }
;                 *(LAS u32x2*)(QL + i * 528 + dq * 2) = (u32x2){pg8::cvt_pk_bf16(qd[0], qd[1]), pg8::cvt_pk_bf16(qd[2], qd[3])};
;                 *(LAS u32x2*)(KL + i * 528 + dq * 2) = (u32x2){pg8::cvt_pk_bf16(ki[0], ki[1]), pg8::cvt_pk_bf16(ki[2], ki[3])}; }
	v_mov_b32_e32 v169, v156
	v_mov_b32_e32 v156, v153
	v_pk_mul_f32 v[152:153], v[0:1], v[156:157]
	v_mov_b32_e32 v156, v154
	v_pk_fma_f32 v[152:153], v[2:3], v[168:169], v[152:153]
	v_mov_b32_e32 v157, v158
	v_pk_fma_f32 v[152:153], v[4:5], v[156:157], v[152:153]
	v_mov_b32_e32 v158, v155
	v_pk_fma_f32 v[152:153], v[6:7], v[158:159], v[152:153]
	s_nop 0
	v_add_f32_e32 v152, v105, v152
	v_add_f32_e32 v156, v152, v153
	s_waitcnt lgkmcnt(0)
	v_mov_b32_e32 v153, v164
	v_mov_b32_e32 v164, v161
	v_mov_b32_e32 v152, v160
	v_pk_mul_f32 v[154:155], v[8:9], v[164:165]
	s_nop 0
	v_pk_fma_f32 v[152:153], v[10:11], v[152:153], v[154:155]
	v_mov_b32_e32 v154, v162
	v_mov_b32_e32 v155, v166
	v_pk_fma_f32 v[152:153], v[12:13], v[154:155], v[152:153]
	v_mov_b32_e32 v166, v163
	v_pk_fma_f32 v[152:153], v[14:15], v[166:167], v[152:153]
	s_nop 0
	v_add_f32_e32 v152, v156, v152
	v_add_f32_e32 v152, v152, v153
	v_min_f32_e32 v153, 0, v152
	v_mul_f32_e64 v152, |v152|, s88
	v_exp_f32_e32 v152, v152
	s_nop 0
	v_add_f32_e32 v152, 1.0, v152
	v_log_f32_e32 v152, v152
	s_nop 0
	v_mul_f32_e32 v154, 0x3f317217, v152
	v_fma_f32 v154, v152, s90, -v154
	v_fmac_f32_e32 v154, 0x3377d1cf, v152
	v_fmac_f32_e32 v154, 0x3f317217, v152
	v_sub_f32_e32 v152, v153, v154
	v_cmp_lt_i32_e32 vcc, 47, v172
	s_or_b64 vcc, s[66:67], vcc
	v_mul_f32_e32 v152, 0x3d800000, v152
	v_cndmask_b32_e32 v152, 0, v152, vcc
	v_add_f32_e32 v152, v170, v152
	v_add_u32_e32 v153, 0x12c00, v171
	s_cmp_eq_u32 s0, 32
	ds_write_b32 v153, v152
	s_cbranch_scc0 .LBB0_1629
	ds_write_b32 v91, v152 offset:4096
	s_waitcnt lgkmcnt(0)
	s_barrier
	ds_read_b128 v[0:3], v128 offset:4096
	ds_read_b128 v[8:11], v128 offset:5120
	v_mov_b32_e32 v4, 0
	v_mov_b32_e32 v5, 0
	v_mov_b32_e32 v6, 0
	v_mov_b32_e32 v7, 0
	s_and_saveexec_b64 s[0:1], s[38:39]
	ds_read_b128 v[4:7], v132
	s_or_b64 exec, exec, s[0:1]
	s_waitcnt lgkmcnt(0)
	v_pk_add_f32 v[150:151], v[0:1], v[8:9]
	s_lshl_b32 s0, s94, 4
	v_pk_add_f32 v[154:155], v[2:3], v[10:11]
	v_cndmask_b32_e64 v14, v9, v151, s[36:37]
	v_cndmask_b32_e64 v9, v3, 0, s[36:37]
	v_add_u32_e32 v3, v130, v129
	s_add_i32 s0, s0, s96
	v_cndmask_b32_e64 v12, v11, v155, s[36:37]
	v_cndmask_b32_e64 v13, v10, v154, s[36:37]
	v_cndmask_b32_e64 v15, v8, v150, s[36:37]
	v_cndmask_b32_e64 v11, v1, 0, s[36:37]
	v_cndmask_b32_e64 v10, v0, 0, s[36:37]
	v_mul_f32_e32 v0, 0x3fb8aa3b, v150
	v_mul_f32_e32 v1, 0x3fb8aa3b, v151
	ds_read_b128 v[150:153], v3
	s_mul_hi_i32 s1, s0, 0x41
	s_mulk_i32 s0, 0x41
	s_ashr_i32 s33, s95, 31
	s_add_u32 s66, s0, s95
	s_addc_u32 s67, s1, s33
	s_add_i32 s0, s93, 0x40f
	s_cmpk_lt_u32 s0, 0x81f
	v_cndmask_b32_e64 v8, v2, 0, s[36:37]
	v_mul_f32_e32 v2, 0x3fb8aa3b, v154
	v_mul_f32_e32 v3, 0x3fb8aa3b, v155
	s_waitcnt lgkmcnt(0)
	v_pk_add_f32 v[154:155], v[10:11], v[150:151]
	v_sub_f32_e32 v159, v15, v4
	v_sub_f32_e32 v160, v14, v5
	s_cselect_b64 s[54:55], -1, 0
	v_sub_f32_e32 v105, v13, v6
	v_sub_f32_e32 v158, v12, v7
	ds_read2st64_b64 v[4:7], v138 offset0:12 offset1:78
	v_cndmask_b32_e64 v155, v160, v155, s[54:55]
	v_cndmask_b32_e64 v154, v159, v154, s[54:55]
	v_mul_f32_e32 v154, 0x3fb8aa3b, v154
	v_mul_f32_e32 v155, 0x3fb8aa3b, v155
	v_exp_f32_e32 v154, v154
	v_exp_f32_e32 v155, v155
	v_pk_add_f32 v[156:157], v[8:9], v[152:153]
	s_waitcnt lgkmcnt(0)
	v_lshlrev_b32_e32 v159, 16, v6
	v_cndmask_b32_e64 v157, v158, v157, s[54:55]
	v_cndmask_b32_e64 v105, v105, v156, s[54:55]
	v_lshlrev_b32_e32 v156, 16, v4
	v_and_b32_e32 v4, 0xffff0000, v4
	v_rcp_f32_e32 v161, v154
	v_mul_f32_e32 v154, v154, v156
	v_rcp_f32_e32 v156, v155
	v_mul_f32_e32 v4, v155, v4
	v_mul_f32_e32 v105, 0x3fb8aa3b, v105
	v_mul_f32_e32 v155, 0x3fb8aa3b, v157
	v_exp_f32_e32 v105, v105
	v_exp_f32_e32 v155, v155
	v_and_b32_e32 v6, 0xffff0000, v6
	v_lshlrev_b32_e32 v158, 16, v5
	v_and_b32_e32 v5, 0xffff0000, v5
	v_mul_f32_e32 v6, v156, v6
	v_rcp_f32_e32 v156, v105
	v_rcp_f32_e32 v157, v155
	v_mul_f32_e32 v5, v155, v5
	v_mul_f32_e32 v4, 0x3d800000, v4
	v_mul_f32_e32 v105, v105, v158
	v_mul_f32_e32 v5, 0x3d800000, v5
	v_lshlrev_b32_e32 v160, 16, v7
	v_and_b32_e32 v7, 0xffff0000, v7
	v_mul_f32_e32 v154, 0x3d800000, v154
	v_mul_f32_e32 v105, 0x3d800000, v105
	v_cvt_pk_bf16_f32 v4, v154, v4
	v_cvt_pk_bf16_f32 v5, v105, v5
	v_mul_f32_e32 v159, v161, v159
	v_mul_f32_e32 v158, v156, v160
	v_mul_f32_e32 v160, v157, v7
	ds_write_b64 v138, v[4:5] offset:6144
	v_cvt_pk_bf16_f32 v4, v159, v6
	v_cvt_pk_bf16_f32 v5, v158, v160
	ds_write_b64 v138, v[4:5] offset:39936
	ds_read_b128 v[154:157], v139
	v_exp_f32_e32 v0, v0
	v_exp_f32_e32 v2, v2
	v_sub_f32_e32 v105, v15, v150
	v_sub_f32_e32 v162, v14, v151
	v_mul_f32_e32 v7, v0, v159
	v_mul_f32_e32 v5, v2, v158
	s_waitcnt lgkmcnt(0)
	v_pk_add_f32 v[158:159], v[10:11], v[154:155]
	v_add_u32_e32 v150, 16, v138
	v_cndmask_b32_e64 v105, v105, v158, s[54:55]
	v_mul_f32_e32 v105, 0x3fb8aa3b, v105
	v_exp_f32_e32 v105, v105
	v_exp_f32_e32 v3, v3
	v_sub_f32_e32 v163, v13, v152
	v_sub_f32_e32 v164, v12, v153
	ds_read2st64_b64 v[150:153], v150 offset0:13 offset1:79
	v_cndmask_b32_e64 v159, v162, v159, s[54:55]
	v_mul_f32_e32 v159, 0x3fb8aa3b, v159
	v_rcp_f32_e32 v165, v105
	v_exp_f32_e32 v159, v159
	v_mul_f32_e32 v4, v3, v160
	v_pk_add_f32 v[160:161], v[8:9], v[156:157]
	s_waitcnt lgkmcnt(0)
; __device__ __forceinline__ unsigned cvt_pk_bf16(float lo, float hi) { unsigned r; asm volatile("v_cvt_pk_bf16_f32 %0, %1, %2" : "=v"(r) : "v"(lo), "v"(hi)); return r; }
; #define LAS __attribute__((address_space(3)))
; __device__ __forceinline__ void gla_prep_phase(const Ctx& c, int j, LAS unsigned char* lds) {
;     ...
;             for (int e = 0; e < 8; ++e) { const int i = i0 + e;
;                 const f32x4 incl = *(const LAS f32x4*)(CUM + i * 256 + dq);
;                 const f32x4 cum = (dir == 0) ? (off0 + incl) : (sbase - prev); prev = incl;
;                 const u32x2 qw = *(const LAS u32x2*)(QL + i * 528 + dq * 2), kw = *(const LAS u32x2*)(KL + i * 528 + dq * 2);
;                 const float qv[4] = {__uint_as_float(qw.x << 16), __uint_as_float(qw.x & 0xffff0000u), __uint_as_float(qw.y << 16), __uint_as_float(qw.y & 0xffff0000u)};
;                 const float kv[4] = {__uint_as_float(kw.x << 16), __uint_as_float(kw.x & 0xffff0000u), __uint_as_float(kw.y << 16), __uint_as_float(kw.y & 0xffff0000u)};
;                 float qd[4], ki[4];
; #pragma unroll
;                 for (int jx = 0; jx < 4; ++jx) { const float ec = __expf(cum[jx]), rc = __builtin_amdgcn_rcpf(ec);
;                     qd[jx] = qv[jx] * ec * (1.f / 16.f); ki[jx] = kv[jx] * rc; kf[jx][e] = ki[jx] * etot[jx]; }
;                 *(LAS u32x2*)(QL + i * 528 + dq * 2) = (u32x2){pg8::cvt_pk_bf16(qd[0], qd[1]), pg8::cvt_pk_bf16(qd[2], qd[3])};
;                 *(LAS u32x2*)(KL + i * 528 + dq * 2) = (u32x2){pg8::cvt_pk_bf16(ki[0], ki[1]), pg8::cvt_pk_bf16(ki[2], ki[3])}; }
	v_lshlrev_b32_e32 v158, 16, v150
	v_cndmask_b32_e64 v160, v163, v160, s[54:55]
	v_lshlrev_b32_e32 v163, 16, v152
	v_mul_f32_e32 v105, v105, v158
	v_mul_f32_e32 v158, v165, v163
	v_rcp_f32_e32 v163, v159
	v_cndmask_b32_e64 v161, v164, v161, s[54:55]
	v_and_b32_e32 v150, 0xffff0000, v150
	v_and_b32_e32 v152, 0xffff0000, v152
	v_mul_f32_e32 v150, v159, v150
	v_mul_f32_e32 v159, 0x3fb8aa3b, v160
	v_mul_f32_e32 v160, v163, v152
	v_mul_f32_e32 v152, 0x3fb8aa3b, v161
	v_exp_f32_e32 v159, v159
	v_exp_f32_e32 v152, v152
	v_lshlrev_b32_e32 v162, 16, v151
	v_and_b32_e32 v151, 0xffff0000, v151
	v_rcp_f32_e32 v161, v159
	v_mul_f32_e32 v159, v159, v162
	v_rcp_f32_e32 v162, v152
	v_mul_f32_e32 v151, v152, v151
	v_mul_f32_e32 v150, 0x3d800000, v150
	v_mul_f32_e32 v151, 0x3d800000, v151
	v_lshlrev_b32_e32 v164, 16, v153
	v_and_b32_e32 v153, 0xffff0000, v153
	v_mul_f32_e32 v105, 0x3d800000, v105
	v_mul_f32_e32 v159, 0x3d800000, v159
	v_cvt_pk_bf16_f32 v150, v105, v150
	v_cvt_pk_bf16_f32 v151, v159, v151
	v_mul_f32_e32 v161, v161, v164
	v_mul_f32_e32 v162, v162, v153
	ds_write_b64 v138, v[150:151] offset:6672
	v_cvt_pk_bf16_f32 v150, v158, v160
	v_cvt_pk_bf16_f32 v151, v161, v162
	ds_write_b64 v138, v[150:151] offset:40464
	ds_read_b128 v[150:153], v140
	v_mul_f32_e32 v163, v0, v158
	v_mul_f32_e32 v105, v3, v162
	v_sub_f32_e32 v162, v15, v154
	v_sub_f32_e32 v166, v14, v155
	s_waitcnt lgkmcnt(0)
	v_pk_add_f32 v[158:159], v[10:11], v[150:151]
	v_add_u32_e32 v154, 32, v138
	v_cndmask_b32_e64 v158, v162, v158, s[54:55]
	v_mul_f32_e32 v158, 0x3fb8aa3b, v158
	v_exp_f32_e32 v158, v158
	v_exp_f32_e32 v1, v1
	v_sub_f32_e32 v167, v13, v156
	v_sub_f32_e32 v168, v12, v157
	ds_read2st64_b64 v[154:157], v154 offset0:14 offset1:80
	v_cndmask_b32_e64 v159, v166, v159, s[54:55]
	v_mul_f32_e32 v159, 0x3fb8aa3b, v159
	v_rcp_f32_e32 v169, v158
	v_exp_f32_e32 v159, v159
	v_mul_f32_e32 v164, v1, v160
	v_mul_f32_e32 v165, v2, v161
	v_pk_add_f32 v[160:161], v[8:9], v[152:153]
	s_waitcnt lgkmcnt(0)
	v_lshlrev_b32_e32 v162, 16, v154
	v_cndmask_b32_e64 v160, v167, v160, s[54:55]
	v_lshlrev_b32_e32 v167, 16, v156
	v_mul_f32_e32 v158, v158, v162
	v_mul_f32_e32 v162, v169, v167
	v_rcp_f32_e32 v167, v159
	v_cndmask_b32_e64 v161, v168, v161, s[54:55]
	v_and_b32_e32 v154, 0xffff0000, v154
	v_and_b32_e32 v156, 0xffff0000, v156
	v_mul_f32_e32 v154, v159, v154
	v_mul_f32_e32 v159, 0x3fb8aa3b, v160
	v_mul_f32_e32 v160, v167, v156
	v_mul_f32_e32 v156, 0x3fb8aa3b, v161
	v_exp_f32_e32 v159, v159
	v_exp_f32_e32 v156, v156
	v_lshlrev_b32_e32 v166, 16, v155
	v_and_b32_e32 v155, 0xffff0000, v155
	v_rcp_f32_e32 v161, v159
	v_mul_f32_e32 v159, v159, v166
	v_rcp_f32_e32 v166, v156
	v_mul_f32_e32 v155, v156, v155
	v_mul_f32_e32 v154, 0x3d800000, v154
	v_mul_f32_e32 v155, 0x3d800000, v155
	v_lshlrev_b32_e32 v168, 16, v157
	v_and_b32_e32 v157, 0xffff0000, v157
	v_mul_f32_e32 v158, 0x3d800000, v158
	v_mul_f32_e32 v159, 0x3d800000, v159
	v_cvt_pk_bf16_f32 v154, v158, v154
	v_cvt_pk_bf16_f32 v155, v159, v155
	v_mul_f32_e32 v161, v161, v168
	v_mul_f32_e32 v166, v166, v157
	ds_write_b64 v138, v[154:155] offset:7200
	v_cvt_pk_bf16_f32 v154, v162, v160
	v_cvt_pk_bf16_f32 v155, v161, v166
	ds_write_b64 v138, v[154:155] offset:40992
	ds_read_b128 v[154:157], v141
	v_sub_f32_e32 v169, v15, v150
	v_sub_f32_e32 v170, v14, v151
	v_add_u32_e32 v150, 48, v138
	v_sub_f32_e32 v171, v13, v152
	s_waitcnt lgkmcnt(0)
	v_pk_add_f32 v[158:159], v[10:11], v[154:155]
	v_sub_f32_e32 v172, v12, v153
	v_cndmask_b32_e64 v158, v169, v158, s[54:55]
	v_mul_f32_e32 v158, 0x3fb8aa3b, v158
	v_exp_f32_e32 v158, v158
	ds_read2st64_b64 v[150:153], v150 offset0:15 offset1:81
	v_cndmask_b32_e64 v159, v170, v159, s[54:55]
	v_mul_f32_e32 v159, 0x3fb8aa3b, v159
	v_rcp_f32_e32 v173, v158
	v_exp_f32_e32 v159, v159
	v_mul_f32_e32 v167, v1, v160
	v_mul_f32_e32 v168, v2, v161
	v_pk_add_f32 v[160:161], v[8:9], v[156:157]
	s_waitcnt lgkmcnt(0)
	v_lshlrev_b32_e32 v169, 16, v150
	v_cndmask_b32_e64 v160, v171, v160, s[54:55]
	v_lshlrev_b32_e32 v171, 16, v152
	v_mul_f32_e32 v158, v158, v169
	v_mul_f32_e32 v169, v173, v171
	v_rcp_f32_e32 v171, v159
	v_cndmask_b32_e64 v161, v172, v161, s[54:55]
	v_and_b32_e32 v150, 0xffff0000, v150
	v_and_b32_e32 v152, 0xffff0000, v152
	v_mul_f32_e32 v150, v159, v150
	v_mul_f32_e32 v159, 0x3fb8aa3b, v160
	v_mul_f32_e32 v160, v171, v152
	v_mul_f32_e32 v152, 0x3fb8aa3b, v161
	v_exp_f32_e32 v159, v159
	v_exp_f32_e32 v152, v152
	v_lshlrev_b32_e32 v170, 16, v151
	v_and_b32_e32 v151, 0xffff0000, v151
	v_rcp_f32_e32 v161, v159
	v_mul_f32_e32 v159, v159, v170
	v_rcp_f32_e32 v170, v152
	v_mul_f32_e32 v151, v152, v151
	v_mul_f32_e32 v150, 0x3d800000, v150
	v_mul_f32_e32 v151, 0x3d800000, v151
	v_lshlrev_b32_e32 v172, 16, v153
	v_and_b32_e32 v153, 0xffff0000, v153
	v_mul_f32_e32 v158, 0x3d800000, v158
	v_mul_f32_e32 v159, 0x3d800000, v159
	v_cvt_pk_bf16_f32 v150, v158, v150
	v_cvt_pk_bf16_f32 v151, v159, v151
	v_mul_f32_e32 v161, v161, v172
	v_mul_f32_e32 v170, v170, v153
	ds_write_b64 v138, v[150:151] offset:7728
	v_cvt_pk_bf16_f32 v150, v169, v160
	v_cvt_pk_bf16_f32 v151, v161, v170
	ds_write_b64 v138, v[150:151] offset:41520
	ds_read_b128 v[150:153], v142
	v_sub_f32_e32 v173, v15, v154
	v_sub_f32_e32 v174, v14, v155
	v_add_u32_e32 v154, 64, v138
	v_sub_f32_e32 v175, v13, v156
	s_waitcnt lgkmcnt(0)
	v_pk_add_f32 v[158:159], v[10:11], v[150:151]
	v_sub_f32_e32 v176, v12, v157
	v_cndmask_b32_e64 v158, v173, v158, s[54:55]
	v_mul_f32_e32 v158, 0x3fb8aa3b, v158
	v_exp_f32_e32 v158, v158
	ds_read2st64_b64 v[154:157], v154 offset0:16 offset1:82
	v_cndmask_b32_e64 v159, v174, v159, s[54:55]
	v_mul_f32_e32 v159, 0x3fb8aa3b, v159
	v_rcp_f32_e32 v177, v158
	v_exp_f32_e32 v159, v159
	v_mul_f32_e32 v171, v1, v160
	v_mul_f32_e32 v172, v2, v161
	v_pk_add_f32 v[160:161], v[8:9], v[152:153]
	s_waitcnt lgkmcnt(0)
; __device__ __forceinline__ unsigned cvt_pk_bf16(float lo, float hi) { unsigned r; asm volatile("v_cvt_pk_bf16_f32 %0, %1, %2" : "=v"(r) : "v"(lo), "v"(hi)); return r; }
; #define LAS __attribute__((address_space(3)))
; __device__ __forceinline__ void gla_prep_phase(const Ctx& c, int j, LAS unsigned char* lds) {
;     ...
;             for (int e = 0; e < 8; ++e) { const int i = i0 + e;
;                 const f32x4 incl = *(const LAS f32x4*)(CUM + i * 256 + dq);
;                 const f32x4 cum = (dir == 0) ? (off0 + incl) : (sbase - prev); prev = incl;
;                 const u32x2 qw = *(const LAS u32x2*)(QL + i * 528 + dq * 2), kw = *(const LAS u32x2*)(KL + i * 528 + dq * 2);
;                 const float qv[4] = {__uint_as_float(qw.x << 16), __uint_as_float(qw.x & 0xffff0000u), __uint_as_float(qw.y << 16), __uint_as_float(qw.y & 0xffff0000u)};
;                 const float kv[4] = {__uint_as_float(kw.x << 16), __uint_as_float(kw.x & 0xffff0000u), __uint_as_float(kw.y << 16), __uint_as_float(kw.y & 0xffff0000u)};
;                 float qd[4], ki[4];
; #pragma unroll
;                 for (int jx = 0; jx < 4; ++jx) { const float ec = __expf(cum[jx]), rc = __builtin_amdgcn_rcpf(ec);
;                     qd[jx] = qv[jx] * ec * (1.f / 16.f); ki[jx] = kv[jx] * rc; kf[jx][e] = ki[jx] * etot[jx]; }
;                 *(LAS u32x2*)(QL + i * 528 + dq * 2) = (u32x2){pg8::cvt_pk_bf16(qd[0], qd[1]), pg8::cvt_pk_bf16(qd[2], qd[3])};
;                 *(LAS u32x2*)(KL + i * 528 + dq * 2) = (u32x2){pg8::cvt_pk_bf16(ki[0], ki[1]), pg8::cvt_pk_bf16(ki[2], ki[3])}; }
	v_lshlrev_b32_e32 v173, 16, v154
	v_cndmask_b32_e64 v160, v175, v160, s[54:55]
	v_lshlrev_b32_e32 v175, 16, v156
	v_mul_f32_e32 v158, v158, v173
	v_mul_f32_e32 v173, v177, v175
	v_rcp_f32_e32 v175, v159
	v_cndmask_b32_e64 v161, v176, v161, s[54:55]
	v_and_b32_e32 v154, 0xffff0000, v154
	v_and_b32_e32 v156, 0xffff0000, v156
	v_mul_f32_e32 v154, v159, v154
	v_mul_f32_e32 v159, 0x3fb8aa3b, v160
	v_mul_f32_e32 v160, v175, v156
	v_mul_f32_e32 v156, 0x3fb8aa3b, v161
	v_exp_f32_e32 v159, v159
	v_exp_f32_e32 v156, v156
	v_lshlrev_b32_e32 v174, 16, v155
	v_and_b32_e32 v155, 0xffff0000, v155
	v_rcp_f32_e32 v161, v159
	v_mul_f32_e32 v159, v159, v174
	v_rcp_f32_e32 v174, v156
	v_mul_f32_e32 v155, v156, v155
	v_mul_f32_e32 v154, 0x3d800000, v154
	v_mul_f32_e32 v155, 0x3d800000, v155
	v_lshlrev_b32_e32 v176, 16, v157
	v_and_b32_e32 v157, 0xffff0000, v157
	v_mul_f32_e32 v158, 0x3d800000, v158
	v_mul_f32_e32 v159, 0x3d800000, v159
	v_cvt_pk_bf16_f32 v154, v158, v154
	v_cvt_pk_bf16_f32 v155, v159, v155
	v_mul_f32_e32 v161, v161, v176
	v_mul_f32_e32 v174, v174, v157
	ds_write_b64 v138, v[154:155] offset:8256
	v_cvt_pk_bf16_f32 v154, v173, v160
	v_cvt_pk_bf16_f32 v155, v161, v174
	ds_write_b64 v138, v[154:155] offset:42048
	ds_read_b128 v[154:157], v143
	v_sub_f32_e32 v177, v15, v150
	v_sub_f32_e32 v178, v14, v151
	v_add_u32_e32 v150, 0x50, v138
	v_sub_f32_e32 v179, v13, v152
	s_waitcnt lgkmcnt(0)
	v_pk_add_f32 v[158:159], v[10:11], v[154:155]
	v_sub_f32_e32 v180, v12, v153
	v_cndmask_b32_e64 v158, v177, v158, s[54:55]
	v_mul_f32_e32 v158, 0x3fb8aa3b, v158
	v_exp_f32_e32 v158, v158
	ds_read2st64_b64 v[150:153], v150 offset0:17 offset1:83
	v_cndmask_b32_e64 v159, v178, v159, s[54:55]
	v_mul_f32_e32 v159, 0x3fb8aa3b, v159
	v_rcp_f32_e32 v181, v158
	v_exp_f32_e32 v159, v159
	v_mul_f32_e32 v175, v1, v160
	v_mul_f32_e32 v176, v2, v161
	v_pk_add_f32 v[160:161], v[8:9], v[156:157]
	s_waitcnt lgkmcnt(0)
	v_lshlrev_b32_e32 v177, 16, v150
	v_cndmask_b32_e64 v160, v179, v160, s[54:55]
	v_lshlrev_b32_e32 v179, 16, v152
	v_mul_f32_e32 v158, v158, v177
	v_mul_f32_e32 v177, v181, v179
	v_rcp_f32_e32 v179, v159
	v_cndmask_b32_e64 v161, v180, v161, s[54:55]
	v_and_b32_e32 v150, 0xffff0000, v150
	v_and_b32_e32 v152, 0xffff0000, v152
	v_mul_f32_e32 v150, v159, v150
	v_mul_f32_e32 v159, 0x3fb8aa3b, v160
	v_mul_f32_e32 v160, v179, v152
	v_mul_f32_e32 v152, 0x3fb8aa3b, v161
	v_exp_f32_e32 v159, v159
	v_exp_f32_e32 v152, v152
	v_lshlrev_b32_e32 v178, 16, v151
	v_and_b32_e32 v151, 0xffff0000, v151
	v_rcp_f32_e32 v161, v159
	v_mul_f32_e32 v159, v159, v178
	v_rcp_f32_e32 v178, v152
	v_mul_f32_e32 v151, v152, v151
	v_mul_f32_e32 v150, 0x3d800000, v150
	v_mul_f32_e32 v151, 0x3d800000, v151
	v_lshlrev_b32_e32 v180, 16, v153
	v_and_b32_e32 v153, 0xffff0000, v153
	v_mul_f32_e32 v158, 0x3d800000, v158
	v_mul_f32_e32 v159, 0x3d800000, v159
	v_cvt_pk_bf16_f32 v150, v158, v150
	v_cvt_pk_bf16_f32 v151, v159, v151
	v_mul_f32_e32 v161, v161, v180
	v_mul_f32_e32 v178, v178, v153
	ds_write_b64 v138, v[150:151] offset:8784
	v_cvt_pk_bf16_f32 v150, v177, v160
	v_cvt_pk_bf16_f32 v151, v161, v178
	ds_write_b64 v138, v[150:151] offset:42576
	ds_read_b128 v[150:153], v144
	v_sub_f32_e32 v181, v15, v154
	v_sub_f32_e32 v182, v14, v155
	v_add_u32_e32 v154, 0x60, v138
	v_sub_f32_e32 v183, v13, v156
	s_waitcnt lgkmcnt(0)
	v_pk_add_f32 v[158:159], v[10:11], v[150:151]
	v_sub_f32_e32 v184, v12, v157
	v_cndmask_b32_e64 v158, v181, v158, s[54:55]
	v_mul_f32_e32 v158, 0x3fb8aa3b, v158
	v_exp_f32_e32 v158, v158
	ds_read2st64_b64 v[154:157], v154 offset0:18 offset1:84
	v_cndmask_b32_e64 v159, v182, v159, s[54:55]
	v_mul_f32_e32 v159, 0x3fb8aa3b, v159
	v_rcp_f32_e32 v185, v158
	v_exp_f32_e32 v159, v159
	v_mul_f32_e32 v179, v1, v160
	v_mul_f32_e32 v180, v2, v161
	v_pk_add_f32 v[160:161], v[8:9], v[152:153]
	s_waitcnt lgkmcnt(0)
; __device__ __forceinline__ unsigned cvt_pk_bf16(float lo, float hi) { unsigned r; asm volatile("v_cvt_pk_bf16_f32 %0, %1, %2" : "=v"(r) : "v"(lo), "v"(hi)); return r; }
; #define LAS __attribute__((address_space(3)))
; __device__ __forceinline__ void gla_prep_phase(const Ctx& c, int j, LAS unsigned char* lds) {
;     ...
;             for (int e = 0; e < 8; ++e) { const int i = i0 + e;
;                 const f32x4 incl = *(const LAS f32x4*)(CUM + i * 256 + dq);
;                 const f32x4 cum = (dir == 0) ? (off0 + incl) : (sbase - prev); prev = incl;
;                 const u32x2 qw = *(const LAS u32x2*)(QL + i * 528 + dq * 2), kw = *(const LAS u32x2*)(KL + i * 528 + dq * 2);
;                 const float qv[4] = {__uint_as_float(qw.x << 16), __uint_as_float(qw.x & 0xffff0000u), __uint_as_float(qw.y << 16), __uint_as_float(qw.y & 0xffff0000u)};
;                 const float kv[4] = {__uint_as_float(kw.x << 16), __uint_as_float(kw.x & 0xffff0000u), __uint_as_float(kw.y << 16), __uint_as_float(kw.y & 0xffff0000u)};
;                 float qd[4], ki[4];
; #pragma unroll
;                 for (int jx = 0; jx < 4; ++jx) { const float ec = __expf(cum[jx]), rc = __builtin_amdgcn_rcpf(ec);
;                     qd[jx] = qv[jx] * ec * (1.f / 16.f); ki[jx] = kv[jx] * rc; kf[jx][e] = ki[jx] * etot[jx]; }
;                 *(LAS u32x2*)(QL + i * 528 + dq * 2) = (u32x2){pg8::cvt_pk_bf16(qd[0], qd[1]), pg8::cvt_pk_bf16(qd[2], qd[3])};
;                 *(LAS u32x2*)(KL + i * 528 + dq * 2) = (u32x2){pg8::cvt_pk_bf16(ki[0], ki[1]), pg8::cvt_pk_bf16(ki[2], ki[3])}; }
;             bf16_t* kdst = KET + tile * (256 * 64) + (size_t)dq * 64 + i0;
; #pragma unroll
;             for (int jx = 0; jx < 4; ++jx)
;                 *(u32x4*)(kdst + jx * 64) = (u32x4){pg8::cvt_pk_bf16(kf[jx][0], kf[jx][1]), pg8::cvt_pk_bf16(kf[jx][2], kf[jx][3]), pg8::cvt_pk_bf16(kf[jx][4], kf[jx][5]), pg8::cvt_pk_bf16(kf[jx][6], kf[jx][7])};
;             if (i0 == 0) *(f32x4*)(DEC + tile * 256 + dq) = etot;
	v_lshlrev_b32_e32 v181, 16, v154
	v_cndmask_b32_e64 v160, v183, v160, s[54:55]
	v_lshlrev_b32_e32 v183, 16, v156
	v_mul_f32_e32 v158, v158, v181
	v_mul_f32_e32 v181, v185, v183
	v_rcp_f32_e32 v183, v159
	v_cndmask_b32_e64 v161, v184, v161, s[54:55]
	v_and_b32_e32 v154, 0xffff0000, v154
	v_and_b32_e32 v156, 0xffff0000, v156
	v_mul_f32_e32 v154, v159, v154
	v_mul_f32_e32 v159, 0x3fb8aa3b, v160
	v_mul_f32_e32 v160, v183, v156
	v_mul_f32_e32 v156, 0x3fb8aa3b, v161
	v_exp_f32_e32 v159, v159
	v_exp_f32_e32 v156, v156
	v_lshlrev_b32_e32 v182, 16, v155
	v_and_b32_e32 v155, 0xffff0000, v155
	v_rcp_f32_e32 v161, v159
	v_mul_f32_e32 v159, v159, v182
	v_rcp_f32_e32 v182, v156
	v_mul_f32_e32 v155, v156, v155
	v_mul_f32_e32 v154, 0x3d800000, v154
	v_mul_f32_e32 v155, 0x3d800000, v155
	v_lshlrev_b32_e32 v184, 16, v157
	v_and_b32_e32 v157, 0xffff0000, v157
	v_mul_f32_e32 v158, 0x3d800000, v158
	v_mul_f32_e32 v159, 0x3d800000, v159
	v_cvt_pk_bf16_f32 v154, v158, v154
	v_cvt_pk_bf16_f32 v155, v159, v155
	v_mul_f32_e32 v161, v161, v184
	v_mul_f32_e32 v182, v182, v157
	ds_write_b64 v138, v[154:155] offset:9312
	v_cvt_pk_bf16_f32 v154, v181, v160
	v_cvt_pk_bf16_f32 v155, v161, v182
	ds_write_b64 v138, v[154:155] offset:43104
	ds_read_b128 v[154:157], v145
	v_sub_f32_e32 v15, v15, v150
	v_sub_f32_e32 v14, v14, v151
	v_sub_f32_e32 v13, v13, v152
	v_sub_f32_e32 v12, v12, v153
	s_waitcnt lgkmcnt(0)
	v_pk_add_f32 v[154:155], v[10:11], v[154:155]
	v_pk_add_f32 v[156:157], v[8:9], v[156:157]
	v_cndmask_b32_e64 v15, v15, v154, s[54:55]
	v_mul_f32_e32 v15, 0x3fb8aa3b, v15
	v_exp_f32_e32 v15, v15
	ds_read2st64_b64 v[8:11], v146 offset0:12 offset1:78
	v_cndmask_b32_e64 v14, v14, v155, s[54:55]
	v_mul_f32_e32 v14, 0x3fb8aa3b, v14
	v_rcp_f32_e32 v154, v15
	v_exp_f32_e32 v14, v14
	v_cndmask_b32_e64 v13, v13, v156, s[54:55]
	s_waitcnt lgkmcnt(0)
	v_lshlrev_b32_e32 v150, 16, v8
	v_lshlrev_b32_e32 v152, 16, v10
	v_mul_f32_e32 v13, 0x3fb8aa3b, v13
	v_mul_f32_e32 v15, v15, v150
	v_mul_f32_e32 v150, v154, v152
	v_rcp_f32_e32 v154, v14
	v_exp_f32_e32 v13, v13
	v_cndmask_b32_e64 v12, v12, v157, s[54:55]
	v_and_b32_e32 v10, 0xffff0000, v10
	v_mul_f32_e32 v12, 0x3fb8aa3b, v12
	v_mul_f32_e32 v10, v154, v10
	v_rcp_f32_e32 v154, v13
	v_exp_f32_e32 v12, v12
	v_lshlrev_b32_e32 v151, 16, v9
	v_lshlrev_b32_e32 v153, 16, v11
	v_and_b32_e32 v8, 0xffff0000, v8
	v_and_b32_e32 v9, 0xffff0000, v9
	v_mul_f32_e32 v13, v13, v151
	v_mul_f32_e32 v151, v154, v153
	v_rcp_f32_e32 v153, v12
	v_mul_f32_e32 v8, v14, v8
	v_mul_f32_e32 v9, v12, v9
	v_mul_f32_e32 v8, 0x3d800000, v8
	v_mul_f32_e32 v9, 0x3d800000, v9
	v_and_b32_e32 v11, 0xffff0000, v11
	v_mul_f32_e32 v15, 0x3d800000, v15
	v_mul_f32_e32 v13, 0x3d800000, v13
	v_cvt_pk_bf16_f32 v8, v15, v8
	v_cvt_pk_bf16_f32 v9, v13, v9
	s_lshl_b64 s[0:1], s[66:67], 15
	v_mul_f32_e32 v6, v1, v6
	v_mul_f32_e32 v11, v153, v11
	ds_write_b64 v146, v[8:9] offset:6144
	v_cvt_pk_bf16_f32 v8, v150, v10
	v_cvt_pk_bf16_f32 v9, v151, v11
	v_lshl_add_u64 v[12:13], v[92:93], 0, s[0:1]
	v_mul_f32_e32 v162, v0, v162
	v_mul_f32_e32 v169, v0, v169
	v_mul_f32_e32 v173, v0, v173
	v_mul_f32_e32 v177, v0, v177
	v_mul_f32_e32 v158, v0, v181
	v_mul_f32_e32 v152, v0, v150
	v_mul_f32_e32 v14, v1, v10
	v_mul_f32_e32 v153, v3, v11
	ds_write_b64 v146, v[8:9] offset:39936
	v_cvt_pk_bf16_f32 v8, v7, v163
	v_cvt_pk_bf16_f32 v9, v162, v169
	v_cvt_pk_bf16_f32 v10, v173, v177
	v_cvt_pk_bf16_f32 v11, v158, v152
	global_store_dwordx4 v[12:13], v[8:11], off
	v_cvt_pk_bf16_f32 v6, v6, v164
	v_cvt_pk_bf16_f32 v7, v167, v171
	v_mul_f32_e32 v159, v1, v160
	v_mul_f32_e32 v166, v3, v166
	v_cvt_pk_bf16_f32 v8, v175, v179
	v_cvt_pk_bf16_f32 v9, v159, v14
	global_store_dwordx4 v[12:13], v[6:9], off offset:128
	v_mul_f32_e32 v170, v3, v170
	v_mul_f32_e32 v174, v3, v174
	v_cvt_pk_bf16_f32 v6, v5, v165
	v_cvt_pk_bf16_f32 v7, v168, v172
	v_mul_f32_e32 v178, v3, v178
	v_mul_f32_e32 v160, v2, v161
	v_mul_f32_e32 v161, v3, v182
	v_mul_f32_e32 v154, v2, v151
	v_cvt_pk_bf16_f32 v8, v176, v180
	v_cvt_pk_bf16_f32 v9, v160, v154
	global_store_dwordx4 v[12:13], v[6:9], off offset:256
	v_cvt_pk_bf16_f32 v4, v4, v105
	v_cvt_pk_bf16_f32 v5, v166, v170
	s_nop 1
	v_cvt_pk_bf16_f32 v6, v174, v178
	v_cvt_pk_bf16_f32 v7, v161, v153
	global_store_dwordx4 v[12:13], v[4:7], off offset:384
	s_and_saveexec_b64 s[0:1], s[52:53]
	s_cbranch_execz .LBB0_1634
	s_lshl_b64 s[58:59], s[66:67], 10
	v_lshl_add_u64 v[4:5], v[94:95], 0, s[58:59]
	global_store_dwordx4 v[4:5], v[0:3], off

.LBB0_1701:
	s_or_b64 exec, exec, s[34:35]
	s_lshl_b32 s0, s87, 2
	s_and_b32 s36, s0, 28
	s_ashr_i32 s22, s87, 6
	s_add_i32 s36, s36, s22
	s_bfe_u32 s40, s36, 0x20002
	s_cmp_lt_u32 s36, 16
	s_cselect_b64 s[34:35], -1, 0
	s_and_b64 s[0:1], s[34:35], exec
	s_mul_i32 s59, s36, 0x41
	s_cselect_b32 s0, 0, 64
	s_mul_hi_i32 s58, s36, 0x41
	s_add_u32 s38, s59, s0
	s_addc_u32 s39, s58, 0
	s_lshl_b64 s[0:1], s[38:39], 15
	s_add_u32 s42, s65, s0
	v_mov_b32_e32 v44, v200
	s_addc_u32 s43, s66, s1
	s_add_u32 s0, s67, s0
	v_ashrrev_i32_e32 v45, 31, v44
	v_lshlrev_b64 v[2:3], 4, v[44:45]
	s_addc_u32 s1, s68, s1
	v_lshl_add_u64 v[4:5], s[42:43], 0, v[2:3]
	v_lshl_add_u64 v[6:7], s[0:1], 0, v[2:3]
	global_load_dwordx4 v[36:39], v[4:5], off
	global_load_dwordx4 v[28:31], v[6:7], off
	s_mov_b64 vcc, s[20:21]
	s_cbranch_vccz .Lscan_kf_b0
	v_lshrrev_b32_e32 v140, 6, v200
	v_lshlrev_b32_e32 v140, 13, v140
	v_and_b32_e32 v141, 31, v200
	v_lshl_add_u32 v140, v141, 7, v140
	v_bfe_u32 v141, v200, 5, 1
	v_lshl_add_u32 v140, v141, 4, v140
	v_lshlrev_b32_e32 v141, 4, v200
	v_sub_u32_e32 v140, v140, v141
	v_add_u32_e32 v140, 0xffff8800, v140
	v_ashrrev_i32_e32 v141, 31, v140
	v_lshl_add_u64 v[142:143], v[140:141], 0, v[6:7]
	global_load_dwordx4 v[112:115], v[142:143], off offset:-2048
	global_load_dwordx4 v[116:119], v[142:143], off offset:-2016
	global_load_dwordx4 v[120:123], v[142:143], off offset:-1984
	global_load_dwordx4 v[124:127], v[142:143], off offset:-1952
	global_load_dwordx4 v[128:131], v[142:143], off offset:2048
	global_load_dwordx4 v[132:135], v[142:143], off offset:2080
	global_load_dwordx4 v[136:139], v[142:143], off offset:2112
	global_load_dwordx4 v[140:143], v[142:143], off offset:2144
.Lscan_kf_b0:
	v_lshl_add_u64 v[4:5], v[2:3], 0, s[26:27]
	v_lshl_add_u64 v[6:7], s[42:43], 0, v[4:5]
	v_lshl_add_u64 v[4:5], s[0:1], 0, v[4:5]
	s_lshl_b64 s[44:45], s[38:39], 13
	global_load_dwordx4 v[32:35], v[6:7], off
	global_load_dwordx4 v[16:19], v[4:5], off
	v_lshl_add_u64 v[4:5], v[2:3], 0, s[28:29]
	s_add_u32 s44, s69, s44
	v_lshl_add_u64 v[6:7], s[42:43], 0, v[4:5]
	v_lshl_add_u64 v[4:5], s[0:1], 0, v[4:5]
	s_addc_u32 s45, s76, s45
	global_load_dwordx4 v[24:27], v[6:7], off
	global_load_dwordx4 v[8:11], v[4:5], off
	v_lshl_add_u64 v[4:5], v[2:3], 0, s[30:31]
	v_lshl_add_u64 v[6:7], s[42:43], 0, v[4:5]
	v_lshl_add_u64 v[4:5], s[0:1], 0, v[4:5]
	v_lshl_add_u64 v[2:3], s[44:45], 0, v[2:3]
	global_load_dwordx4 v[20:23], v[6:7], off
	s_nop 0
	global_load_dwordx4 v[4:7], v[4:5], off
	s_cmp_gt_u32 s36, 15
	global_load_dwordx4 v[12:15], v[2:3], off
	v_and_b32_e32 v1, 63, v44
	s_mov_b64 s[0:1], -1
	s_cbranch_scc0 .LBB0_1703
	v_lshl_or_b32 v2, s40, 12, v1
	v_or_b32_e32 v2, 0xfc0, v2
	s_mov_b64 s[0:1], 0

; __device__ __forceinline__ int mk_tid() { int t = (int)threadIdx.x; asm volatile("" : "+v"(t)); return t; }
; __device__ __forceinline__ void gla_scan_phase(const Ctx& c, LAS unsigned char* lds) {
;     ...
;         { const int c0 = dir ? NCH - 1 : 0; SC_LOAD(c0, mk_tid()); SC_STORE(mk_tid()); SC_LOAD(dir ? NCH - 2 : 1, mk_tid()); }
.LBB0_1707:
	s_or_b64 exec, exec, s[0:1]
	v_mov_b32_e32 v45, v200
	s_nop 0
	v_lshlrev_b32_e32 v1, 4, v45
	v_and_b32_e32 v2, 0x1f0, v1
	v_add_u32_e32 v2, 0, v2
	v_ashrrev_i32_e32 v3, 5, v45
	v_mad_u64_u32 v[46:47], s[0:1], v3, s81, v[2:3]
	v_and_b32_e32 v48, 0x70, v1
	s_waitcnt vmcnt(9)
	ds_write_b128 v46, v[36:39]
	v_ashrrev_i32_e32 v36, 3, v45
	v_add_u32_e32 v44, 0, v48
	v_mul_lo_u32 v37, v36, s79
	v_add_u32_e32 v3, v44, v37
	s_waitcnt vmcnt(8)
	ds_write_b128 v3, v[28:31] offset:33792
	v_add_u32_e32 v3, 0x200, v45
	v_ashrrev_i32_e32 v28, 5, v3
	v_mad_u64_u32 v[28:29], s[0:1], v28, s81, v[2:3]
	v_lshrrev_b32_e32 v3, 3, v3
	s_waitcnt vmcnt(7)
	ds_write_b128 v28, v[32:35]
	v_mad_u64_u32 v[28:29], s[0:1], v3, s79, v[44:45]
	v_add_u32_e32 v3, 0x400, v45
	s_waitcnt vmcnt(6)
	ds_write_b128 v28, v[16:19] offset:33792
	v_ashrrev_i32_e32 v16, 5, v3
	v_mad_u64_u32 v[16:17], s[0:1], v16, s81, v[2:3]
	v_lshrrev_b32_e32 v3, 3, v3
	s_waitcnt vmcnt(5)
	ds_write_b128 v16, v[24:27]
	v_mad_u64_u32 v[16:17], s[0:1], v3, s79, v[44:45]
	s_waitcnt vmcnt(4)
	ds_write_b128 v16, v[8:11] offset:33792
	v_add_u32_e32 v8, 0x600, v45
	v_ashrrev_i32_e32 v3, 5, v8
	v_mad_u64_u32 v[2:3], s[0:1], v3, s81, v[2:3]
	s_waitcnt vmcnt(3)
	ds_write_b128 v2, v[20:23]
	v_lshrrev_b32_e32 v2, 3, v8
	v_mad_u64_u32 v[2:3], s[0:1], v2, s79, v[44:45]
	s_waitcnt vmcnt(2)
	ds_write_b128 v2, v[4:7] offset:33792
	v_add3_u32 v2, s82, v37, v48
	s_waitcnt vmcnt(1)
	ds_write_b128 v2, v[12:15]
	v_lshlrev_b32_e32 v2, 1, v45
	v_and_b32_e32 v2, 0x7e, v2
	v_and_b32_e32 v3, 0xffffff8, v36
	v_add_u32_e32 v2, s80, v2
	v_mad_u64_u32 v[4:5], s[0:1], v3, s79, v[2:3]
	v_or_b32_e32 v3, 7, v36
	v_mad_u64_u32 v[2:3], s[0:1], v3, s79, v[2:3]
	v_cmp_gt_i32_e32 vcc, 64, v45
	s_waitcnt vmcnt(0)
	ds_write_b16 v4, v40
	ds_write_b16_d16_hi v4, v40 offset:144
	ds_write_b16 v4, v41 offset:288
	ds_write_b16_d16_hi v4, v41 offset:432
	ds_write_b16 v4, v42 offset:576
	ds_write_b16_d16_hi v4, v42 offset:720
	ds_write_b16 v4, v43 offset:864
	ds_write_b16_d16_hi v2, v43
	s_and_saveexec_b64 s[0:1], vcc
	v_add_u32_e32 v1, 0, v1
	v_add_u32_e32 v1, 0x1e000, v1
	ds_write_b128 v1, v[148:151]
	s_or_b64 exec, exec, s[0:1]
	s_and_b64 s[0:1], s[34:35], exec
	s_cselect_b32 s37, 1, 63
	s_add_u32 s38, s59, s37
	s_addc_u32 s39, s58, 0
	s_lshl_b64 s[0:1], s[38:39], 15
	v_mov_b32_e32 v2, v200
	s_add_u32 s44, s65, s0
	s_addc_u32 s45, s66, s1
	v_ashrrev_i32_e32 v3, 31, v2
	s_add_u32 s0, s67, s0
	v_lshlrev_b64 v[4:5], 4, v[2:3]
	s_addc_u32 s1, s68, s1
	v_lshl_add_u64 v[6:7], s[44:45], 0, v[4:5]
	v_lshl_add_u64 v[8:9], s[0:1], 0, v[4:5]
	global_load_dwordx4 v[152:155], v[6:7], off
	global_load_dwordx4 v[156:159], v[8:9], off
	s_mov_b64 vcc, s[20:21]
	s_cbranch_vccz .Lscan_kf_b1
	v_lshrrev_b32_e32 v250, 6, v200
	v_lshlrev_b32_e32 v250, 13, v250
	v_and_b32_e32 v251, 31, v200
	v_lshl_add_u32 v250, v251, 7, v250
	v_bfe_u32 v251, v200, 5, 1
	v_lshl_add_u32 v250, v251, 4, v250
	v_lshlrev_b32_e32 v251, 4, v200
	v_sub_u32_e32 v250, v250, v251
	v_add_u32_e32 v250, 0xffff8800, v250
	v_ashrrev_i32_e32 v251, 31, v250
	v_lshl_add_u64 v[252:253], v[250:251], 0, v[8:9]
	global_load_dwordx4 v[222:225], v[252:253], off offset:-2048
	global_load_dwordx4 v[226:229], v[252:253], off offset:-2016
	global_load_dwordx4 v[230:233], v[252:253], off offset:-1984
	global_load_dwordx4 v[234:237], v[252:253], off offset:-1952
	global_load_dwordx4 v[238:241], v[252:253], off offset:2048
	global_load_dwordx4 v[242:245], v[252:253], off offset:2080
	global_load_dwordx4 v[246:249], v[252:253], off offset:2112
	global_load_dwordx4 v[250:253], v[252:253], off offset:2144
.Lscan_kf_b1:
	v_lshl_add_u64 v[6:7], v[4:5], 0, s[26:27]
	v_lshl_add_u64 v[8:9], s[44:45], 0, v[6:7]
	v_lshl_add_u64 v[6:7], s[0:1], 0, v[6:7]
	global_load_dwordx4 v[160:163], v[8:9], off
	global_load_dwordx4 v[164:167], v[6:7], off
	v_lshl_add_u64 v[6:7], v[4:5], 0, s[28:29]
	v_lshl_add_u64 v[8:9], s[44:45], 0, v[6:7]
	v_lshl_add_u64 v[6:7], s[0:1], 0, v[6:7]
	global_load_dwordx4 v[168:171], v[8:9], off
	global_load_dwordx4 v[172:175], v[6:7], off
	v_lshl_add_u64 v[6:7], v[4:5], 0, s[30:31]
	v_lshl_add_u64 v[8:9], s[44:45], 0, v[6:7]
	v_lshl_add_u64 v[6:7], s[0:1], 0, v[6:7]
	s_lshl_b64 s[0:1], s[38:39], 13
	s_add_u32 s0, s69, s0
	s_addc_u32 s1, s76, s1
	v_lshl_add_u64 v[4:5], s[0:1], 0, v[4:5]
	s_lshl_b32 s0, s37, 6
	s_sub_i32 s0, s0, 64
	s_lshl_b32 s43, s40, 12
	v_and_or_b32 v1, v2, 63, s0
	v_or_b32_e32 v1, s43, v1
	v_mul_u32_u24_e32 v1, 0x1820, v1
	global_load_dwordx4 v[176:179], v[8:9], off
	global_load_dwordx4 v[180:183], v[6:7], off
	v_lshlrev_b32_e32 v6, 1, v1
	v_mov_b32_e32 v7, v0
	v_lshl_add_u64 v[6:7], s[16:17], 0, v[6:7]
	v_ashrrev_i32_e32 v1, 3, v2
	v_lshl_add_u64 v[6:7], v[6:7], 0, s[22:23]
	s_mov_b32 s37, s23
	v_and_b32_e32 v8, -8, v1
	v_lshl_add_u64 v[6:7], v[6:7], 0, s[36:37]
	v_ashrrev_i32_e32 v9, 31, v8
	v_lshl_add_u64 v[6:7], v[8:9], 1, v[6:7]
	v_add_co_u32_e32 v6, vcc, 0x1000, v6
	s_nop 1
	v_addc_co_u32_e32 v7, vcc, 0, v7, vcc
	global_load_dwordx4 v[184:187], v[4:5], off
	global_load_dwordx4 v[188:191], v[6:7], off
	v_cmp_gt_i32_e32 vcc, 64, v2
	s_and_saveexec_b64 s[0:1], vcc
	s_cbranch_execz .LBB0_1711
	s_lshl_b64 s[38:39], s[38:39], 10
	s_add_u32 s38, s77, s38
	v_lshlrev_b32_e32 v2, 2, v2
	s_addc_u32 s39, s78, s39
	v_ashrrev_i32_e32 v3, 31, v2
	v_lshl_add_u64 v[2:3], v[2:3], 2, s[38:39]
	global_load_dwordx4 v[148:151], v[2:3], off

; #define LAS __attribute__((address_space(3)))
; __device__ __forceinline__ void gla_scan_phase(const Ctx& c, LAS unsigned char* lds) {
;     ...
;             } else {
;                 const int jj = wid - 4;
;                 __builtin_amdgcn_s_setprio(2);
; #pragma unroll
;                 for (int t = 0; t < 4; ++t) { const int db = 2 * jj + (t >> 1);
; #pragma unroll
;                     for (int g4 = 0; g4 < 4; ++g4) { const f32x4 dv = *(const LAS f32x4*)(lds + SC_DEC + (32 * db + 8 * g4 + 4 * hi) * 4);
;                         sacc[t][4 * g4 + 0] *= dv.x; sacc[t][4 * g4 + 1] *= dv.y; sacc[t][4 * g4 + 2] *= dv.z; sacc[t][4 * g4 + 3] *= dv.w; } }
; #pragma unroll
;                 for (int ks = 0; ks < 4; ++ks) {
;                     const bf16x8 a0 = *(const LAS bf16x8*)(lds + SC_KT + (64 * jj + r32) * 144 + (ks * 16 + hi * 8) * 2);
;                     const bf16x8 a1 = *(const LAS bf16x8*)(lds + SC_KT + (64 * jj + 32 + r32) * 144 + (ks * 16 + hi * 8) * 2);
;                     const bf16x8 b0 = *(const LAS bf16x8*)(lds + SC_VT + r32 * 144 + (ks * 16 + hi * 8) * 2);
;                     const bf16x8 b1 = *(const LAS bf16x8*)(lds + SC_VT + (32 + r32) * 144 + (ks * 16 + hi * 8) * 2);
;                     sacc[0] = __builtin_amdgcn_mfma_f32_32x32x16_bf16(a0, b0, sacc[0], 0, 0, 0);
;                     sacc[1] = __builtin_amdgcn_mfma_f32_32x32x16_bf16(a0, b1, sacc[1], 0, 0, 0);
;                     sacc[2] = __builtin_amdgcn_mfma_f32_32x32x16_bf16(a1, b0, sacc[2], 0, 0, 0);
;                     sacc[3] = __builtin_amdgcn_mfma_f32_32x32x16_bf16(a1, b1, sacc[3], 0, 0, 0); }
;             }
.LBB0_1714:
	s_mov_b64 s[60:61], -1
	s_and_b64 vcc, exec, s[20:21]
	s_cbranch_vccz .LBB0_1716
	s_setprio 2
	s_mov_b64 s[60:61], 0
	ds_read_b128 v[80:83], v205
	ds_read_b128 v[84:87], v205 offset:32
	ds_read_b128 v[88:91], v205 offset:64
	ds_read_b128 v[92:95], v205 offset:96
	ds_read_b128 v[96:99], v205 offset:128
	ds_read_b128 v[100:103], v205 offset:160
	ds_read_b128 v[104:107], v205 offset:192
	ds_read_b128 v[108:111], v205 offset:224
	ds_read_b128 v[210:213], v207
	ds_read_b128 v[214:217], v207 offset:4608
	ds_read_b128 v[218:221], v207 offset:32
	ds_read_b128 v[2:5], v207 offset:4640
	s_waitcnt lgkmcnt(8)
	v_pk_mul_f32 v[64:65], v[64:65], v[80:81]
	v_pk_mul_f32 v[66:67], v[66:67], v[82:83]
	v_pk_mul_f32 v[68:69], v[68:69], v[84:85]
	v_pk_mul_f32 v[70:71], v[70:71], v[86:87]
	v_pk_mul_f32 v[72:73], v[72:73], v[88:89]
	v_pk_mul_f32 v[74:75], v[74:75], v[90:91]
	v_pk_mul_f32 v[76:77], v[76:77], v[92:93]
	v_pk_mul_f32 v[78:79], v[78:79], v[94:95]
	v_pk_mul_f32 v[48:49], v[48:49], v[80:81]
	v_pk_mul_f32 v[50:51], v[50:51], v[82:83]
	v_pk_mul_f32 v[52:53], v[52:53], v[84:85]
	v_pk_mul_f32 v[54:55], v[54:55], v[86:87]
	v_pk_mul_f32 v[56:57], v[56:57], v[88:89]
	v_pk_mul_f32 v[58:59], v[58:59], v[90:91]
	v_pk_mul_f32 v[60:61], v[60:61], v[92:93]
	v_pk_mul_f32 v[62:63], v[62:63], v[94:95]
	ds_read_b128 v[80:83], v207 offset:64
	ds_read_b128 v[84:87], v207 offset:4672
	ds_read_b128 v[88:91], v207 offset:96
	ds_read_b128 v[92:95], v207 offset:4704
	s_waitcnt lgkmcnt(8)
	v_pk_mul_f32 v[32:33], v[32:33], v[96:97]
	v_pk_mul_f32 v[34:35], v[34:35], v[98:99]
	v_pk_mul_f32 v[36:37], v[36:37], v[100:101]
	v_pk_mul_f32 v[38:39], v[38:39], v[102:103]
	v_pk_mul_f32 v[40:41], v[40:41], v[104:105]
	v_pk_mul_f32 v[42:43], v[42:43], v[106:107]
	v_pk_mul_f32 v[44:45], v[44:45], v[108:109]
	v_pk_mul_f32 v[46:47], v[46:47], v[110:111]
	v_pk_mul_f32 v[16:17], v[16:17], v[96:97]
	v_pk_mul_f32 v[18:19], v[18:19], v[98:99]
	v_pk_mul_f32 v[20:21], v[20:21], v[100:101]
	v_pk_mul_f32 v[22:23], v[22:23], v[102:103]
	v_pk_mul_f32 v[24:25], v[24:25], v[104:105]
	v_pk_mul_f32 v[26:27], v[26:27], v[106:107]
	v_pk_mul_f32 v[28:29], v[28:29], v[108:109]
	v_pk_mul_f32 v[30:31], v[30:31], v[110:111]
	s_waitcnt lgkmcnt(4)
	v_mfma_f32_32x32x16_bf16 v[64:79], v[112:115], v[210:213], v[64:79]
	v_mfma_f32_32x32x16_bf16 v[48:63], v[112:115], v[214:217], v[48:63]
	v_mfma_f32_32x32x16_bf16 v[32:47], v[128:131], v[210:213], v[32:47]
	v_mfma_f32_32x32x16_bf16 v[16:31], v[128:131], v[214:217], v[16:31]
	v_mfma_f32_32x32x16_bf16 v[64:79], v[116:119], v[218:221], v[64:79]
	v_mfma_f32_32x32x16_bf16 v[48:63], v[116:119], v[2:5], v[48:63]
	v_mfma_f32_32x32x16_bf16 v[32:47], v[132:135], v[218:221], v[32:47]
	v_mfma_f32_32x32x16_bf16 v[16:31], v[132:135], v[2:5], v[16:31]
	s_waitcnt lgkmcnt(0)
	v_mfma_f32_32x32x16_bf16 v[64:79], v[120:123], v[80:83], v[64:79]
	v_mfma_f32_32x32x16_bf16 v[48:63], v[120:123], v[84:87], v[48:63]
	v_mfma_f32_32x32x16_bf16 v[32:47], v[136:139], v[80:83], v[32:47]
	v_mfma_f32_32x32x16_bf16 v[16:31], v[136:139], v[84:87], v[16:31]
	v_mfma_f32_32x32x16_bf16 v[64:79], v[124:127], v[88:91], v[64:79]
	v_mfma_f32_32x32x16_bf16 v[48:63], v[124:127], v[92:95], v[48:63]
	v_mfma_f32_32x32x16_bf16 v[32:47], v[140:143], v[88:91], v[32:47]
	v_mfma_f32_32x32x16_bf16 v[16:31], v[140:143], v[92:95], v[16:31]

; __device__ __forceinline__ int mk_tid() { int t = (int)threadIdx.x; asm volatile("" : "+v"(t)); return t; }
; __device__ __forceinline__ void gla_scan_phase(const Ctx& c, LAS unsigned char* lds) {
;     ...
;             if (st + 1 < NCH) SC_STORE(mk_tid());
;             if (st + 2 < NCH) SC_LOAD(chn2, mk_tid());
.LBB0_1722:
	s_cmp_eq_u32 s92, 64
	s_cbranch_scc1 .LBB0_1726
	v_mov_b32_e32 v86, v200
	s_nop 0
	v_lshlrev_b32_e32 v1, 4, v86
	v_and_b32_e32 v80, 0x1f0, v1
	v_and_b32_e32 v83, 0x70, v1
	v_ashrrev_i32_e32 v87, 3, v86
	v_add_u32_e32 v80, 0, v80
	v_add_u32_e32 v82, 0, v83
	v_ashrrev_i32_e32 v81, 5, v86
	v_mul_lo_u32 v88, v87, s79
	v_mad_u64_u32 v[84:85], s[0:1], v81, s81, v[80:81]
	v_add_u32_e32 v81, v82, v88
	s_waitcnt vmcnt(0)
	ds_write_b128 v84, v[152:155]
	s_waitcnt vmcnt(8)
	v_add_u32_e32 v81, 0x200, v86
	v_ashrrev_i32_e32 v84, 5, v81
	v_mad_u64_u32 v[84:85], s[0:1], v84, s81, v[80:81]
	v_lshrrev_b32_e32 v81, 3, v81
	s_waitcnt vmcnt(7)
	ds_write_b128 v84, v[160:163]
	v_mad_u64_u32 v[84:85], s[0:1], v81, s79, v[82:83]
	v_add_u32_e32 v81, 0x400, v86
	s_waitcnt vmcnt(6)
	v_ashrrev_i32_e32 v84, 5, v81
	v_mad_u64_u32 v[84:85], s[0:1], v84, s81, v[80:81]
	v_lshrrev_b32_e32 v81, 3, v81
	s_waitcnt vmcnt(5)
	ds_write_b128 v84, v[168:171]
	v_mad_u64_u32 v[84:85], s[0:1], v81, s79, v[82:83]
	s_waitcnt vmcnt(4)
	v_add_u32_e32 v84, 0x600, v86
	v_ashrrev_i32_e32 v81, 5, v84
	v_mad_u64_u32 v[80:81], s[0:1], v81, s81, v[80:81]
	s_waitcnt vmcnt(3)
	ds_write_b128 v80, v[176:179]
	v_lshrrev_b32_e32 v80, 3, v84
	v_mad_u64_u32 v[80:81], s[0:1], v80, s79, v[82:83]
	s_waitcnt vmcnt(2)
	v_add3_u32 v80, s82, v88, v83
	s_waitcnt vmcnt(1)
	ds_write_b128 v80, v[184:187]
	v_lshlrev_b32_e32 v80, 1, v86
	v_and_b32_e32 v80, 0x7e, v80
	v_and_b32_e32 v81, 0xffffff8, v87
	v_add_u32_e32 v80, s80, v80
	v_mad_u64_u32 v[82:83], s[0:1], v81, s79, v[80:81]
	v_or_b32_e32 v81, 7, v87
	v_mad_u64_u32 v[80:81], s[0:1], v81, s79, v[80:81]
	v_cmp_gt_i32_e32 vcc, 64, v86
	s_waitcnt vmcnt(0)
	ds_write_b16 v82, v188
	ds_write_b16_d16_hi v82, v188 offset:144
	ds_write_b16 v82, v189 offset:288
	ds_write_b16_d16_hi v82, v189 offset:432
	ds_write_b16 v82, v190 offset:576
	ds_write_b16_d16_hi v82, v190 offset:720
	ds_write_b16 v82, v191 offset:864
	ds_write_b16_d16_hi v80, v191
	s_and_saveexec_b64 s[0:1], vcc
	v_add_u32_e32 v1, 0, v1
	v_add_u32_e32 v1, 0x1e000, v1
	ds_write_b128 v1, v[148:151]
	s_or_b64 exec, exec, s[0:1]
.LBB0_1726:
	v_mov_b64_e32 v[112:113], v[222:223]
	v_mov_b64_e32 v[114:115], v[224:225]
	v_mov_b64_e32 v[116:117], v[226:227]
	v_mov_b64_e32 v[118:119], v[228:229]
	v_mov_b64_e32 v[120:121], v[230:231]
	v_mov_b64_e32 v[122:123], v[232:233]
	v_mov_b64_e32 v[124:125], v[234:235]
	v_mov_b64_e32 v[126:127], v[236:237]
	v_mov_b64_e32 v[128:129], v[238:239]
	v_mov_b64_e32 v[130:131], v[240:241]
	v_mov_b64_e32 v[132:133], v[242:243]
	v_mov_b64_e32 v[134:135], v[244:245]
	v_mov_b64_e32 v[136:137], v[246:247]
	v_mov_b64_e32 v[138:139], v[248:249]
	v_mov_b64_e32 v[140:141], v[250:251]
	v_mov_b64_e32 v[142:143], v[252:253]
	s_sub_i32 s37, 64, s92
	s_and_b64 s[0:1], s[34:35], exec
	s_cselect_b32 s62, s92, s37
	s_cmp_gt_u32 s92, 62
	s_cbranch_scc1 .LBB0_1733
	s_add_i32 s0, s62, s88
	s_ashr_i32 s1, s0, 31
	s_add_u32 s60, s59, s0
	s_addc_u32 s61, s58, s1
	s_lshl_b64 s[94:95], s[60:61], 15
	v_mov_b32_e32 v80, v200
	s_add_u32 s96, s65, s94
	s_addc_u32 s97, s66, s95
	v_ashrrev_i32_e32 v81, 31, v80
	s_add_u32 s94, s67, s94
	v_lshlrev_b64 v[82:83], 4, v[80:81]
	s_addc_u32 s95, s68, s95
	v_lshl_add_u64 v[84:85], s[96:97], 0, v[82:83]
	v_lshl_add_u64 v[86:87], s[94:95], 0, v[82:83]
	global_load_dwordx4 v[152:155], v[84:85], off
	s_mov_b64 vcc, s[20:21]
	s_cbranch_vccz .Lscan_kf_b2
	v_lshrrev_b32_e32 v250, 6, v200
	v_lshlrev_b32_e32 v250, 13, v250
	v_and_b32_e32 v251, 31, v200
	v_lshl_add_u32 v250, v251, 7, v250
	v_bfe_u32 v251, v200, 5, 1
	v_lshl_add_u32 v250, v251, 4, v250
	v_lshlrev_b32_e32 v251, 4, v200
	v_sub_u32_e32 v250, v250, v251
	v_add_u32_e32 v250, 0xffff8800, v250
	v_ashrrev_i32_e32 v251, 31, v250
	v_lshl_add_u64 v[252:253], v[250:251], 0, v[86:87]
	global_load_dwordx4 v[222:225], v[252:253], off offset:-2048
	global_load_dwordx4 v[226:229], v[252:253], off offset:-2016
	global_load_dwordx4 v[230:233], v[252:253], off offset:-1984
	global_load_dwordx4 v[234:237], v[252:253], off offset:-1952
	global_load_dwordx4 v[238:241], v[252:253], off offset:2048
	global_load_dwordx4 v[242:245], v[252:253], off offset:2080
	global_load_dwordx4 v[246:249], v[252:253], off offset:2112
	global_load_dwordx4 v[250:253], v[252:253], off offset:2144
.Lscan_kf_b2:
	v_lshl_add_u64 v[84:85], v[82:83], 0, s[26:27]
	v_lshl_add_u64 v[86:87], s[96:97], 0, v[84:85]
	v_lshl_add_u64 v[84:85], s[94:95], 0, v[84:85]
	global_load_dwordx4 v[160:163], v[86:87], off
	v_lshl_add_u64 v[84:85], v[82:83], 0, s[28:29]
	v_lshl_add_u64 v[86:87], s[96:97], 0, v[84:85]
	v_lshl_add_u64 v[84:85], s[94:95], 0, v[84:85]
	global_load_dwordx4 v[168:171], v[86:87], off
	v_lshl_add_u64 v[84:85], v[82:83], 0, s[30:31]
	v_lshl_add_u64 v[86:87], s[96:97], 0, v[84:85]
	v_lshl_add_u64 v[84:85], s[94:95], 0, v[84:85]
	s_lshl_b64 s[94:95], s[60:61], 13
	s_add_u32 s94, s69, s94
	s_addc_u32 s95, s76, s95
	v_lshl_add_u64 v[82:83], s[94:95], 0, v[82:83]
	global_load_dwordx4 v[176:179], v[86:87], off
	global_load_dwordx4 v[184:187], v[82:83], off
	s_cmp_lg_u32 s0, 0
	v_and_b32_e32 v1, 63, v80
	s_cbranch_scc0 .LBB0_1755
	s_lshl_b32 s0, s0, 6
	s_add_i32 s0, s0, s89
	v_or_b32_e32 v81, s0, v1
	s_cbranch_execnz .LBB0_1730
